# E56: GEMM K-loops: the first 4 MFMAs of each compute segment issued before the segment's opening barrier (operands already resident), to keep the matrix pipe busy across the half-to-half barrier hand-
# speedup vs baseline: 1.0009x; 1.0009x over previous
.LBB0_202:
	ds_read_b128 v[146:149], v157
	ds_read_b128 v[150:153], v157 offset:1024
	ds_read_b128 v[164:167], v157 offset:2048
	ds_read_b128 v[168:171], v157 offset:3072
	ds_read_b128 v[172:175], v158
	ds_read_b128 v[176:179], v158 offset:1024
	ds_read_b128 v[180:183], v158 offset:2048
	ds_read_b128 v[184:187], v158 offset:3072
	s_add_u32 s72, s76, 0xfffc0080
	s_addc_u32 s73, s77, -1
	s_cmp_eq_u32 s71, 12
	s_cselect_b32 s85, s5, s73
	s_cselect_b32 s84, s43, s72
	s_cselect_b32 s79, s41, s70
	s_cselect_b32 s78, s49, s69
	v_lshl_add_u64 v[188:189], s[76:77], 0, v[138:139]
	s_add_i32 m0, s93, 0xc000
	ds_read_b128 v[192:195], v159
	ds_read_b128 v[196:199], v159 offset:1024
	ds_read_b128 v[200:203], v159 offset:2048
	ds_read_b128 v[204:207], v159 offset:3072
	ds_read_b128 v[208:211], v159 offset:4096
	ds_read_b128 v[218:221], v159 offset:5120
	ds_read_b128 v[224:227], v159 offset:6144
	ds_read_b128 v[228:231], v159 offset:7168
	global_load_lds_dwordx4 v[188:189], off
	v_lshl_add_u64 v[188:189], s[76:77], 0, v[140:141]
	s_add_i32 m0, s93, 0xe000
	s_nop 0
	global_load_lds_dwordx4 v[188:189], off
	s_waitcnt vmcnt(8)
	s_waitcnt lgkmcnt(0)
	v_mfma_f32_16x16x32_bf16 v[126:129], v[146:149], v[192:195], v[126:129]
	v_mfma_f32_16x16x32_bf16 v[122:125], v[164:167], v[192:195], v[122:125]
	v_mfma_f32_16x16x32_bf16 v[110:113], v[146:149], v[200:203], v[110:113]
	v_mfma_f32_16x16x32_bf16 v[106:109], v[164:167], v[200:203], v[106:109]
	s_barrier
	s_setprio 1
	s_waitcnt lgkmcnt(0)
	v_mfma_f32_16x16x32_bf16 v[94:97], v[146:149], v[208:211], v[94:97]
	v_mfma_f32_16x16x32_bf16 v[90:93], v[164:167], v[208:211], v[90:93]
	v_mfma_f32_16x16x32_bf16 v[78:81], v[146:149], v[224:227], v[78:81]
	v_mfma_f32_16x16x32_bf16 v[74:77], v[164:167], v[224:227], v[74:77]
	v_mfma_f32_16x16x32_bf16 v[126:129], v[150:153], v[196:199], v[126:129]
	v_mfma_f32_16x16x32_bf16 v[122:125], v[168:171], v[196:199], v[122:125]
	v_mfma_f32_16x16x32_bf16 v[110:113], v[150:153], v[204:207], v[110:113]
	v_mfma_f32_16x16x32_bf16 v[106:109], v[168:171], v[204:207], v[106:109]
	v_mfma_f32_16x16x32_bf16 v[94:97], v[150:153], v[218:221], v[94:97]
	v_mfma_f32_16x16x32_bf16 v[90:93], v[168:171], v[218:221], v[90:93]
	v_mfma_f32_16x16x32_bf16 v[78:81], v[150:153], v[228:231], v[78:81]
	v_mfma_f32_16x16x32_bf16 v[74:77], v[168:171], v[228:231], v[74:77]
	v_mfma_f32_16x16x32_bf16 v[118:121], v[172:175], v[192:195], v[118:121]
	v_mfma_f32_16x16x32_bf16 v[114:117], v[180:183], v[192:195], v[114:117]
	v_mfma_f32_16x16x32_bf16 v[102:105], v[172:175], v[200:203], v[102:105]
	v_mfma_f32_16x16x32_bf16 v[98:101], v[180:183], v[200:203], v[98:101]
	v_mfma_f32_16x16x32_bf16 v[86:89], v[172:175], v[208:211], v[86:89]
	v_mfma_f32_16x16x32_bf16 v[82:85], v[180:183], v[208:211], v[82:85]
	v_mfma_f32_16x16x32_bf16 v[70:73], v[172:175], v[224:227], v[70:73]
	v_mfma_f32_16x16x32_bf16 v[66:69], v[180:183], v[224:227], v[66:69]
	v_mfma_f32_16x16x32_bf16 v[118:121], v[176:179], v[196:199], v[118:121]
	v_mfma_f32_16x16x32_bf16 v[114:117], v[184:187], v[196:199], v[114:117]
	v_mfma_f32_16x16x32_bf16 v[102:105], v[176:179], v[204:207], v[102:105]
	v_mfma_f32_16x16x32_bf16 v[98:101], v[184:187], v[204:207], v[98:101]
	v_mfma_f32_16x16x32_bf16 v[86:89], v[176:179], v[218:221], v[86:89]
	v_mfma_f32_16x16x32_bf16 v[82:85], v[184:187], v[218:221], v[82:85]
	v_mfma_f32_16x16x32_bf16 v[70:73], v[176:179], v[228:231], v[70:73]
	v_mfma_f32_16x16x32_bf16 v[66:69], v[184:187], v[228:231], v[66:69]
	s_setprio 0
	s_barrier
	s_add_i32 s72, s67, s92
	v_lshl_add_u64 v[188:189], s[78:79], 0, v[132:133]
	s_mov_b32 m0, s72
	ds_read_b128 v[192:195], v159 offset:16384
	ds_read_b128 v[196:199], v159 offset:17408
	ds_read_b128 v[200:203], v159 offset:18432
	ds_read_b128 v[204:207], v159 offset:19456
	ds_read_b128 v[208:211], v159 offset:20480
	ds_read_b128 v[218:221], v159 offset:21504
	ds_read_b128 v[224:227], v159 offset:22528
	ds_read_b128 v[228:231], v159 offset:23552
	global_load_lds_dwordx4 v[188:189], off
	s_add_i32 m0, s72, 0x2000
	s_add_u32 s72, s78, 0x40000
	v_lshl_add_u64 v[214:215], s[78:79], 0, v[136:137]
	s_addc_u32 s73, s79, 0
	s_add_i32 s74, s68, s92
	global_load_lds_dwordx4 v[214:215], off
	v_lshl_add_u64 v[232:233], s[72:73], 0, v[132:133]
	s_mov_b32 m0, s74
	v_lshl_add_u64 v[234:235], s[84:85], 0, v[134:135]
	global_load_lds_dwordx4 v[232:233], off
	v_lshl_add_u64 v[232:233], s[72:73], 0, v[136:137]
	s_add_i32 m0, s74, 0x2000
	s_nop 0
	global_load_lds_dwordx4 v[232:233], off
	v_lshl_add_u64 v[232:233], s[84:85], 0, v[130:131]
	s_mov_b32 m0, s93
	s_nop 0
	global_load_lds_dwordx4 v[232:233], off
	s_mov_b32 m0, s94
	s_nop 0
	global_load_lds_dwordx4 v[234:235], off
	s_waitcnt vmcnt(8)
	s_waitcnt lgkmcnt(0)
	v_mfma_f32_16x16x32_bf16 v[62:65], v[146:149], v[192:195], v[62:65]
	v_mfma_f32_16x16x32_bf16 v[58:61], v[164:167], v[192:195], v[58:61]
	v_mfma_f32_16x16x32_bf16 v[46:49], v[146:149], v[200:203], v[46:49]
	v_mfma_f32_16x16x32_bf16 v[42:45], v[164:167], v[200:203], v[42:45]
	s_barrier
	s_setprio 1
	s_waitcnt lgkmcnt(0)
	v_mfma_f32_16x16x32_bf16 v[30:33], v[146:149], v[208:211], v[30:33]
	v_mfma_f32_16x16x32_bf16 v[26:29], v[164:167], v[208:211], v[26:29]
	v_mfma_f32_16x16x32_bf16 v[14:17], v[146:149], v[224:227], v[14:17]
	v_mfma_f32_16x16x32_bf16 v[10:13], v[164:167], v[224:227], v[10:13]
	v_mfma_f32_16x16x32_bf16 v[62:65], v[150:153], v[196:199], v[62:65]
	v_mfma_f32_16x16x32_bf16 v[58:61], v[168:171], v[196:199], v[58:61]
	v_mfma_f32_16x16x32_bf16 v[46:49], v[150:153], v[204:207], v[46:49]
	v_mfma_f32_16x16x32_bf16 v[42:45], v[168:171], v[204:207], v[42:45]
	v_mfma_f32_16x16x32_bf16 v[30:33], v[150:153], v[218:221], v[30:33]
	v_mfma_f32_16x16x32_bf16 v[26:29], v[168:171], v[218:221], v[26:29]
	v_mfma_f32_16x16x32_bf16 v[14:17], v[150:153], v[228:231], v[14:17]
	v_mfma_f32_16x16x32_bf16 v[10:13], v[168:171], v[228:231], v[10:13]
	v_mfma_f32_16x16x32_bf16 v[54:57], v[172:175], v[192:195], v[54:57]
	v_mfma_f32_16x16x32_bf16 v[50:53], v[180:183], v[192:195], v[50:53]
	v_mfma_f32_16x16x32_bf16 v[38:41], v[172:175], v[200:203], v[38:41]
	v_mfma_f32_16x16x32_bf16 v[34:37], v[180:183], v[200:203], v[34:37]
	v_mfma_f32_16x16x32_bf16 v[22:25], v[172:175], v[208:211], v[22:25]
	v_mfma_f32_16x16x32_bf16 v[18:21], v[180:183], v[208:211], v[18:21]
	v_mfma_f32_16x16x32_bf16 v[6:9], v[172:175], v[224:227], v[6:9]
	v_mfma_f32_16x16x32_bf16 v[2:5], v[180:183], v[224:227], v[2:5]
	v_mfma_f32_16x16x32_bf16 v[54:57], v[176:179], v[196:199], v[54:57]
	v_mfma_f32_16x16x32_bf16 v[50:53], v[184:187], v[196:199], v[50:53]
	v_mfma_f32_16x16x32_bf16 v[38:41], v[176:179], v[204:207], v[38:41]
	v_mfma_f32_16x16x32_bf16 v[34:37], v[184:187], v[204:207], v[34:37]
	v_mfma_f32_16x16x32_bf16 v[22:25], v[176:179], v[218:221], v[22:25]
	v_mfma_f32_16x16x32_bf16 v[18:21], v[184:187], v[218:221], v[18:21]
	v_mfma_f32_16x16x32_bf16 v[6:9], v[176:179], v[228:231], v[6:9]
	v_mfma_f32_16x16x32_bf16 v[2:5], v[184:187], v[228:231], v[2:5]
	s_setprio 0
	s_barrier
	s_add_i32 s74, 0, 0x18000
	v_add_u32_e32 v161, s74, v155
	s_add_i32 s75, 0, 0x1c000
	ds_read_b128 v[146:149], v161
	ds_read_b128 v[150:153], v161 offset:1024
	ds_read_b128 v[164:167], v161 offset:2048
	ds_read_b128 v[168:171], v161 offset:3072
	v_add_u32_e32 v161, s75, v155
	ds_read_b128 v[172:175], v161
	ds_read_b128 v[176:179], v161 offset:1024
	ds_read_b128 v[180:183], v161 offset:2048
	ds_read_b128 v[184:187], v161 offset:3072
	s_add_u32 s72, s84, 0x40000
	s_addc_u32 s73, s85, 0
	s_mov_b32 m0, s95
	v_lshl_add_u64 v[236:237], s[72:73], 0, v[130:131]
	ds_read_b128 v[192:195], v159 offset:32768
	ds_read_b128 v[196:199], v159 offset:33792
	ds_read_b128 v[200:203], v159 offset:34816
	ds_read_b128 v[204:207], v159 offset:35840
	ds_read_b128 v[208:211], v159 offset:36864
	ds_read_b128 v[218:221], v159 offset:37888
	ds_read_b128 v[224:227], v159 offset:38912
	ds_read_b128 v[228:231], v159 offset:39936
	global_load_lds_dwordx4 v[236:237], off
	v_lshl_add_u64 v[236:237], s[72:73], 0, v[134:135]
	s_mov_b32 m0, s96
	s_nop 0
	global_load_lds_dwordx4 v[236:237], off
	s_waitcnt vmcnt(8)
	s_waitcnt lgkmcnt(0)
	v_mfma_f32_16x16x32_bf16 v[126:129], v[146:149], v[192:195], v[126:129]
	v_mfma_f32_16x16x32_bf16 v[122:125], v[164:167], v[192:195], v[122:125]
	v_mfma_f32_16x16x32_bf16 v[110:113], v[146:149], v[200:203], v[110:113]
	v_mfma_f32_16x16x32_bf16 v[106:109], v[164:167], v[200:203], v[106:109]
	s_barrier
	s_setprio 1
	s_waitcnt lgkmcnt(0)
	v_mfma_f32_16x16x32_bf16 v[94:97], v[146:149], v[208:211], v[94:97]
	v_mfma_f32_16x16x32_bf16 v[90:93], v[164:167], v[208:211], v[90:93]
	v_mfma_f32_16x16x32_bf16 v[78:81], v[146:149], v[224:227], v[78:81]
	v_mfma_f32_16x16x32_bf16 v[74:77], v[164:167], v[224:227], v[74:77]
	v_mfma_f32_16x16x32_bf16 v[126:129], v[150:153], v[196:199], v[126:129]
	v_mfma_f32_16x16x32_bf16 v[122:125], v[168:171], v[196:199], v[122:125]
	v_mfma_f32_16x16x32_bf16 v[110:113], v[150:153], v[204:207], v[110:113]
	v_mfma_f32_16x16x32_bf16 v[106:109], v[168:171], v[204:207], v[106:109]
	v_mfma_f32_16x16x32_bf16 v[94:97], v[150:153], v[218:221], v[94:97]
	v_mfma_f32_16x16x32_bf16 v[90:93], v[168:171], v[218:221], v[90:93]
	v_mfma_f32_16x16x32_bf16 v[78:81], v[150:153], v[228:231], v[78:81]
	v_mfma_f32_16x16x32_bf16 v[74:77], v[168:171], v[228:231], v[74:77]
	v_mfma_f32_16x16x32_bf16 v[118:121], v[172:175], v[192:195], v[118:121]
	v_mfma_f32_16x16x32_bf16 v[114:117], v[180:183], v[192:195], v[114:117]
	v_mfma_f32_16x16x32_bf16 v[102:105], v[172:175], v[200:203], v[102:105]
	v_mfma_f32_16x16x32_bf16 v[98:101], v[180:183], v[200:203], v[98:101]
	v_mfma_f32_16x16x32_bf16 v[86:89], v[172:175], v[208:211], v[86:89]
	v_mfma_f32_16x16x32_bf16 v[82:85], v[180:183], v[208:211], v[82:85]
	v_mfma_f32_16x16x32_bf16 v[70:73], v[172:175], v[224:227], v[70:73]
	v_mfma_f32_16x16x32_bf16 v[66:69], v[180:183], v[224:227], v[66:69]
	v_mfma_f32_16x16x32_bf16 v[118:121], v[176:179], v[196:199], v[118:121]
	v_mfma_f32_16x16x32_bf16 v[114:117], v[184:187], v[196:199], v[114:117]
	v_mfma_f32_16x16x32_bf16 v[102:105], v[176:179], v[204:207], v[102:105]
	v_mfma_f32_16x16x32_bf16 v[98:101], v[184:187], v[204:207], v[98:101]
	v_mfma_f32_16x16x32_bf16 v[86:89], v[176:179], v[218:221], v[86:89]
	v_mfma_f32_16x16x32_bf16 v[82:85], v[184:187], v[218:221], v[82:85]
	v_mfma_f32_16x16x32_bf16 v[70:73], v[176:179], v[228:231], v[70:73]
	v_mfma_f32_16x16x32_bf16 v[66:69], v[184:187], v[228:231], v[66:69]
	s_setprio 0
	s_barrier
	s_add_i32 s72, s74, s92
	v_lshl_add_u64 v[188:189], v[188:189], 0, s[36:37]
	s_mov_b32 m0, s72
	ds_read_b128 v[192:195], v159 offset:49152
	ds_read_b128 v[196:199], v159 offset:50176
	ds_read_b128 v[200:203], v159 offset:51200
	ds_read_b128 v[204:207], v159 offset:52224
	ds_read_b128 v[208:211], v159 offset:53248
	ds_read_b128 v[218:221], v159 offset:54272
	ds_read_b128 v[224:227], v159 offset:55296
	ds_read_b128 v[228:231], v159 offset:56320
	global_load_lds_dwordx4 v[188:189], off
	s_add_i32 m0, s72, 0x2000
	s_add_u32 s72, s78, 0x40080
	v_lshl_add_u64 v[188:189], v[214:215], 0, s[36:37]
	s_addc_u32 s73, s79, 0
	s_add_i32 s74, s75, s92
	global_load_lds_dwordx4 v[188:189], off
	v_lshl_add_u64 v[188:189], s[72:73], 0, v[132:133]
	s_mov_b32 m0, s74
	s_nop 0
	global_load_lds_dwordx4 v[188:189], off
	v_lshl_add_u64 v[188:189], s[72:73], 0, v[136:137]
	s_add_i32 m0, s74, 0x2000
	s_nop 0
	global_load_lds_dwordx4 v[188:189], off
	v_lshl_add_u64 v[188:189], v[232:233], 0, s[36:37]
	s_mov_b32 m0, s86
	s_nop 0
	global_load_lds_dwordx4 v[188:189], off
	v_lshl_add_u64 v[188:189], v[234:235], 0, s[36:37]
	s_mov_b32 m0, s87
	s_nop 0
	global_load_lds_dwordx4 v[188:189], off
	s_waitcnt vmcnt(8)
	s_waitcnt lgkmcnt(0)
	v_mfma_f32_16x16x32_bf16 v[62:65], v[146:149], v[192:195], v[62:65]
	v_mfma_f32_16x16x32_bf16 v[58:61], v[164:167], v[192:195], v[58:61]
	v_mfma_f32_16x16x32_bf16 v[46:49], v[146:149], v[200:203], v[46:49]
	v_mfma_f32_16x16x32_bf16 v[42:45], v[164:167], v[200:203], v[42:45]
	s_barrier
	s_setprio 1
	s_waitcnt lgkmcnt(0)
	v_mfma_f32_16x16x32_bf16 v[30:33], v[146:149], v[208:211], v[30:33]
	v_mfma_f32_16x16x32_bf16 v[26:29], v[164:167], v[208:211], v[26:29]
	v_mfma_f32_16x16x32_bf16 v[14:17], v[146:149], v[224:227], v[14:17]
	v_mfma_f32_16x16x32_bf16 v[10:13], v[164:167], v[224:227], v[10:13]
	v_mfma_f32_16x16x32_bf16 v[62:65], v[150:153], v[196:199], v[62:65]
	v_mfma_f32_16x16x32_bf16 v[58:61], v[168:171], v[196:199], v[58:61]
	v_mfma_f32_16x16x32_bf16 v[46:49], v[150:153], v[204:207], v[46:49]
	v_mfma_f32_16x16x32_bf16 v[42:45], v[168:171], v[204:207], v[42:45]
	v_mfma_f32_16x16x32_bf16 v[30:33], v[150:153], v[218:221], v[30:33]
	v_mfma_f32_16x16x32_bf16 v[26:29], v[168:171], v[218:221], v[26:29]
	v_mfma_f32_16x16x32_bf16 v[14:17], v[150:153], v[228:231], v[14:17]
	v_mfma_f32_16x16x32_bf16 v[10:13], v[168:171], v[228:231], v[10:13]
	v_mfma_f32_16x16x32_bf16 v[54:57], v[172:175], v[192:195], v[54:57]
	v_mfma_f32_16x16x32_bf16 v[50:53], v[180:183], v[192:195], v[50:53]
	v_mfma_f32_16x16x32_bf16 v[38:41], v[172:175], v[200:203], v[38:41]
	v_mfma_f32_16x16x32_bf16 v[34:37], v[180:183], v[200:203], v[34:37]
	v_mfma_f32_16x16x32_bf16 v[22:25], v[172:175], v[208:211], v[22:25]
	v_mfma_f32_16x16x32_bf16 v[18:21], v[180:183], v[208:211], v[18:21]
	v_mfma_f32_16x16x32_bf16 v[6:9], v[172:175], v[224:227], v[6:9]
	v_mfma_f32_16x16x32_bf16 v[2:5], v[180:183], v[224:227], v[2:5]
	v_mfma_f32_16x16x32_bf16 v[54:57], v[176:179], v[196:199], v[54:57]
	v_mfma_f32_16x16x32_bf16 v[50:53], v[184:187], v[196:199], v[50:53]
	v_mfma_f32_16x16x32_bf16 v[38:41], v[176:179], v[204:207], v[38:41]
	v_mfma_f32_16x16x32_bf16 v[34:37], v[184:187], v[204:207], v[34:37]
	v_mfma_f32_16x16x32_bf16 v[22:25], v[176:179], v[218:221], v[22:25]
	v_mfma_f32_16x16x32_bf16 v[18:21], v[184:187], v[218:221], v[18:21]
	v_mfma_f32_16x16x32_bf16 v[6:9], v[176:179], v[228:231], v[6:9]
	v_mfma_f32_16x16x32_bf16 v[2:5], v[184:187], v[228:231], v[2:5]
	s_setprio 0
	s_barrier
	s_add_i32 s71, s71, 2
	s_add_u32 s76, s76, 0x100
	s_addc_u32 s77, s77, 0
	s_add_u32 s69, s69, 0x100
	s_addc_u32 s70, s70, 0
	s_cmp_gt_u32 s71, 13
	s_cbranch_scc0 .LBB0_202
	s_and_b64 vcc, exec, s[38:39]
	s_cbranch_vccz .LBB0_205
	s_barrier

.LBB0_679:
	v_add_u32_e32 v168, s47, v153
	v_add_u32_e32 v184, s48, v153
	s_add_u32 s30, s16, s28
	ds_read_b128 v[156:159], v168
	ds_read_b128 v[160:163], v168 offset:1024
	ds_read_b128 v[164:167], v168 offset:2048
	ds_read_b128 v[168:171], v168 offset:3072
	ds_read_b128 v[172:175], v184
	ds_read_b128 v[176:179], v184 offset:1024
	ds_read_b128 v[180:183], v184 offset:2048
	ds_read_b128 v[184:187], v184 offset:3072
	s_addc_u32 s31, s17, s29
	s_add_u32 s30, s30, 0x100
	s_addc_u32 s31, s31, 0
	s_add_u32 s61, s50, s28
	s_addc_u32 s64, s51, s29
	s_cmpk_eq_i32 s28, 0x700
	s_cselect_b32 s35, s23, s31
	s_cselect_b32 s34, s58, s30
	s_cselect_b32 s31, s21, s64
	s_cselect_b32 s30, s59, s61
	v_lshl_add_u64 v[188:189], v[148:149], 0, s[28:29]
	s_add_i32 m0, s13, 0xc000
	ds_read_b128 v[192:195], v154
	ds_read_b128 v[196:199], v154 offset:1024
	ds_read_b128 v[200:203], v154 offset:2048
	ds_read_b128 v[204:207], v154 offset:3072
	ds_read_b128 v[208:211], v154 offset:4096
	ds_read_b128 v[218:221], v154 offset:5120
	ds_read_b128 v[226:229], v154 offset:6144
	ds_read_b128 v[230:233], v154 offset:7168
	global_load_lds_dwordx4 v[188:189], off
	v_lshl_add_u64 v[188:189], v[150:151], 0, s[28:29]
	s_add_i32 m0, s13, 0xe000
	s_nop 0
	global_load_lds_dwordx4 v[188:189], off
	s_waitcnt vmcnt(8)
	s_waitcnt lgkmcnt(0)
	v_mfma_f32_16x16x32_bf16 v[128:131], v[156:159], v[192:195], v[128:131]
	v_mfma_f32_16x16x32_bf16 v[124:127], v[164:167], v[192:195], v[124:127]
	v_mfma_f32_16x16x32_bf16 v[112:115], v[156:159], v[200:203], v[112:115]
	v_mfma_f32_16x16x32_bf16 v[108:111], v[164:167], v[200:203], v[108:111]
	s_barrier
	s_setprio 1
	s_waitcnt lgkmcnt(0)
	v_mfma_f32_16x16x32_bf16 v[96:99], v[156:159], v[208:211], v[96:99]
	v_mfma_f32_16x16x32_bf16 v[92:95], v[164:167], v[208:211], v[92:95]
	v_mfma_f32_16x16x32_bf16 v[80:83], v[156:159], v[226:229], v[80:83]
	v_mfma_f32_16x16x32_bf16 v[76:79], v[164:167], v[226:229], v[76:79]
	v_mfma_f32_16x16x32_bf16 v[128:131], v[160:163], v[196:199], v[128:131]
	v_mfma_f32_16x16x32_bf16 v[124:127], v[168:171], v[196:199], v[124:127]
	v_mfma_f32_16x16x32_bf16 v[112:115], v[160:163], v[204:207], v[112:115]
	v_mfma_f32_16x16x32_bf16 v[108:111], v[168:171], v[204:207], v[108:111]
	v_mfma_f32_16x16x32_bf16 v[96:99], v[160:163], v[218:221], v[96:99]
	v_mfma_f32_16x16x32_bf16 v[92:95], v[168:171], v[218:221], v[92:95]
	v_mfma_f32_16x16x32_bf16 v[80:83], v[160:163], v[230:233], v[80:83]
	v_mfma_f32_16x16x32_bf16 v[76:79], v[168:171], v[230:233], v[76:79]
	v_mfma_f32_16x16x32_bf16 v[120:123], v[172:175], v[192:195], v[120:123]
	v_mfma_f32_16x16x32_bf16 v[116:119], v[180:183], v[192:195], v[116:119]
	v_mfma_f32_16x16x32_bf16 v[104:107], v[172:175], v[200:203], v[104:107]
	v_mfma_f32_16x16x32_bf16 v[100:103], v[180:183], v[200:203], v[100:103]
	v_mfma_f32_16x16x32_bf16 v[88:91], v[172:175], v[208:211], v[88:91]
	v_mfma_f32_16x16x32_bf16 v[84:87], v[180:183], v[208:211], v[84:87]
	v_mfma_f32_16x16x32_bf16 v[72:75], v[172:175], v[226:229], v[72:75]
	v_mfma_f32_16x16x32_bf16 v[68:71], v[180:183], v[226:229], v[68:71]
	v_mfma_f32_16x16x32_bf16 v[120:123], v[176:179], v[196:199], v[120:123]
	v_mfma_f32_16x16x32_bf16 v[116:119], v[184:187], v[196:199], v[116:119]
	v_mfma_f32_16x16x32_bf16 v[104:107], v[176:179], v[204:207], v[104:107]
	v_mfma_f32_16x16x32_bf16 v[100:103], v[184:187], v[204:207], v[100:103]
	v_mfma_f32_16x16x32_bf16 v[88:91], v[176:179], v[218:221], v[88:91]
	v_mfma_f32_16x16x32_bf16 v[84:87], v[184:187], v[218:221], v[84:87]
	v_mfma_f32_16x16x32_bf16 v[72:75], v[176:179], v[230:233], v[72:75]
	v_mfma_f32_16x16x32_bf16 v[68:71], v[184:187], v[230:233], v[68:71]
	s_setprio 0
	s_barrier
	s_add_i32 s61, s47, s40
	v_lshl_add_u64 v[188:189], s[30:31], 0, v[134:135]
	s_mov_b32 m0, s61
	ds_read_b128 v[192:195], v154 offset:16384
	ds_read_b128 v[196:199], v154 offset:17408
	ds_read_b128 v[200:203], v154 offset:18432
	ds_read_b128 v[204:207], v154 offset:19456
	ds_read_b128 v[208:211], v154 offset:20480
	ds_read_b128 v[218:221], v154 offset:21504
	ds_read_b128 v[226:229], v154 offset:22528
	ds_read_b128 v[230:233], v154 offset:23552
	global_load_lds_dwordx4 v[188:189], off
	s_add_i32 m0, s61, 0x2000
	s_add_u32 s64, s30, 0x40000
	v_lshl_add_u64 v[234:235], s[30:31], 0, v[138:139]
	s_addc_u32 s65, s31, 0
	s_add_i32 s61, s48, s40
	global_load_lds_dwordx4 v[234:235], off
	v_lshl_add_u64 v[236:237], s[64:65], 0, v[134:135]
	s_mov_b32 m0, s61
	v_lshl_add_u64 v[238:239], s[34:35], 0, v[136:137]
	global_load_lds_dwordx4 v[236:237], off
	v_lshl_add_u64 v[236:237], s[64:65], 0, v[138:139]
	s_add_i32 m0, s61, 0x2000
	s_nop 0
	global_load_lds_dwordx4 v[236:237], off
	v_lshl_add_u64 v[236:237], s[34:35], 0, v[132:133]
	s_mov_b32 m0, s13
	s_nop 0
	global_load_lds_dwordx4 v[236:237], off
	s_mov_b32 m0, s41
	s_nop 0
	global_load_lds_dwordx4 v[238:239], off
	s_waitcnt vmcnt(8)
	s_waitcnt lgkmcnt(0)
	v_mfma_f32_16x16x32_bf16 v[64:67], v[156:159], v[192:195], v[64:67]
	v_mfma_f32_16x16x32_bf16 v[60:63], v[164:167], v[192:195], v[60:63]
	v_mfma_f32_16x16x32_bf16 v[48:51], v[156:159], v[200:203], v[48:51]
	v_mfma_f32_16x16x32_bf16 v[44:47], v[164:167], v[200:203], v[44:47]
	s_barrier
	s_setprio 1
	s_waitcnt lgkmcnt(0)
	v_mfma_f32_16x16x32_bf16 v[32:35], v[156:159], v[208:211], v[32:35]
	v_mfma_f32_16x16x32_bf16 v[28:31], v[164:167], v[208:211], v[28:31]
	v_mfma_f32_16x16x32_bf16 v[16:19], v[156:159], v[226:229], v[16:19]
	v_mfma_f32_16x16x32_bf16 v[12:15], v[164:167], v[226:229], v[12:15]
	v_mfma_f32_16x16x32_bf16 v[64:67], v[160:163], v[196:199], v[64:67]
	v_mfma_f32_16x16x32_bf16 v[60:63], v[168:171], v[196:199], v[60:63]
	v_mfma_f32_16x16x32_bf16 v[48:51], v[160:163], v[204:207], v[48:51]
	v_mfma_f32_16x16x32_bf16 v[44:47], v[168:171], v[204:207], v[44:47]
	v_mfma_f32_16x16x32_bf16 v[32:35], v[160:163], v[218:221], v[32:35]
	v_mfma_f32_16x16x32_bf16 v[28:31], v[168:171], v[218:221], v[28:31]
	v_mfma_f32_16x16x32_bf16 v[16:19], v[160:163], v[230:233], v[16:19]
	v_mfma_f32_16x16x32_bf16 v[12:15], v[168:171], v[230:233], v[12:15]
	v_mfma_f32_16x16x32_bf16 v[56:59], v[172:175], v[192:195], v[56:59]
	v_mfma_f32_16x16x32_bf16 v[52:55], v[180:183], v[192:195], v[52:55]
	v_mfma_f32_16x16x32_bf16 v[40:43], v[172:175], v[200:203], v[40:43]
	v_mfma_f32_16x16x32_bf16 v[36:39], v[180:183], v[200:203], v[36:39]
	v_mfma_f32_16x16x32_bf16 v[24:27], v[172:175], v[208:211], v[24:27]
	v_mfma_f32_16x16x32_bf16 v[20:23], v[180:183], v[208:211], v[20:23]
	v_mfma_f32_16x16x32_bf16 v[8:11], v[172:175], v[226:229], v[8:11]
	v_mfma_f32_16x16x32_bf16 v[4:7], v[180:183], v[226:229], v[4:7]
	v_mfma_f32_16x16x32_bf16 v[56:59], v[176:179], v[196:199], v[56:59]
	v_mfma_f32_16x16x32_bf16 v[52:55], v[184:187], v[196:199], v[52:55]
	v_mfma_f32_16x16x32_bf16 v[40:43], v[176:179], v[204:207], v[40:43]
	v_mfma_f32_16x16x32_bf16 v[36:39], v[184:187], v[204:207], v[36:39]
	v_mfma_f32_16x16x32_bf16 v[24:27], v[176:179], v[218:221], v[24:27]
	v_mfma_f32_16x16x32_bf16 v[20:23], v[184:187], v[218:221], v[20:23]
	v_mfma_f32_16x16x32_bf16 v[8:11], v[176:179], v[230:233], v[8:11]
	v_mfma_f32_16x16x32_bf16 v[4:7], v[184:187], v[230:233], v[4:7]
	s_setprio 0
	s_barrier
	s_add_i32 s61, 0, 0x18000
	s_add_i32 s64, 0, 0x1c000
	v_add_u32_e32 v168, s61, v153
	v_add_u32_e32 v184, s64, v153
	ds_read_b128 v[156:159], v168
	ds_read_b128 v[160:163], v168 offset:1024
	ds_read_b128 v[164:167], v168 offset:2048
	ds_read_b128 v[168:171], v168 offset:3072
	ds_read_b128 v[172:175], v184
	ds_read_b128 v[176:179], v184 offset:1024
	ds_read_b128 v[180:183], v184 offset:2048
	ds_read_b128 v[184:187], v184 offset:3072
	s_add_u32 s34, s34, 0x40000
	s_addc_u32 s35, s35, 0
	s_mov_b32 m0, s42
	v_lshl_add_u64 v[240:241], s[34:35], 0, v[132:133]
	ds_read_b128 v[192:195], v154 offset:32768
	ds_read_b128 v[196:199], v154 offset:33792
	ds_read_b128 v[200:203], v154 offset:34816
	ds_read_b128 v[204:207], v154 offset:35840
	ds_read_b128 v[208:211], v154 offset:36864
	ds_read_b128 v[218:221], v154 offset:37888
	ds_read_b128 v[226:229], v154 offset:38912
	ds_read_b128 v[230:233], v154 offset:39936
	global_load_lds_dwordx4 v[240:241], off
	v_lshl_add_u64 v[240:241], s[34:35], 0, v[136:137]
	s_mov_b32 m0, s43
	s_nop 0
	global_load_lds_dwordx4 v[240:241], off
	s_waitcnt vmcnt(8)
	s_waitcnt lgkmcnt(0)
	v_mfma_f32_16x16x32_bf16 v[128:131], v[156:159], v[192:195], v[128:131]
	v_mfma_f32_16x16x32_bf16 v[124:127], v[164:167], v[192:195], v[124:127]
	v_mfma_f32_16x16x32_bf16 v[112:115], v[156:159], v[200:203], v[112:115]
	v_mfma_f32_16x16x32_bf16 v[108:111], v[164:167], v[200:203], v[108:111]
	s_barrier
	s_setprio 1
	s_waitcnt lgkmcnt(0)
	v_mfma_f32_16x16x32_bf16 v[96:99], v[156:159], v[208:211], v[96:99]
	v_mfma_f32_16x16x32_bf16 v[92:95], v[164:167], v[208:211], v[92:95]
	v_mfma_f32_16x16x32_bf16 v[80:83], v[156:159], v[226:229], v[80:83]
	v_mfma_f32_16x16x32_bf16 v[76:79], v[164:167], v[226:229], v[76:79]
	v_mfma_f32_16x16x32_bf16 v[128:131], v[160:163], v[196:199], v[128:131]
	v_mfma_f32_16x16x32_bf16 v[124:127], v[168:171], v[196:199], v[124:127]
	v_mfma_f32_16x16x32_bf16 v[112:115], v[160:163], v[204:207], v[112:115]
	v_mfma_f32_16x16x32_bf16 v[108:111], v[168:171], v[204:207], v[108:111]
	v_mfma_f32_16x16x32_bf16 v[96:99], v[160:163], v[218:221], v[96:99]
	v_mfma_f32_16x16x32_bf16 v[92:95], v[168:171], v[218:221], v[92:95]
	v_mfma_f32_16x16x32_bf16 v[80:83], v[160:163], v[230:233], v[80:83]
	v_mfma_f32_16x16x32_bf16 v[76:79], v[168:171], v[230:233], v[76:79]
	v_mfma_f32_16x16x32_bf16 v[120:123], v[172:175], v[192:195], v[120:123]
	v_mfma_f32_16x16x32_bf16 v[116:119], v[180:183], v[192:195], v[116:119]
	v_mfma_f32_16x16x32_bf16 v[104:107], v[172:175], v[200:203], v[104:107]
	v_mfma_f32_16x16x32_bf16 v[100:103], v[180:183], v[200:203], v[100:103]
	v_mfma_f32_16x16x32_bf16 v[88:91], v[172:175], v[208:211], v[88:91]
	v_mfma_f32_16x16x32_bf16 v[84:87], v[180:183], v[208:211], v[84:87]
	v_mfma_f32_16x16x32_bf16 v[72:75], v[172:175], v[226:229], v[72:75]
	v_mfma_f32_16x16x32_bf16 v[68:71], v[180:183], v[226:229], v[68:71]
	v_mfma_f32_16x16x32_bf16 v[120:123], v[176:179], v[196:199], v[120:123]
	v_mfma_f32_16x16x32_bf16 v[116:119], v[184:187], v[196:199], v[116:119]
	v_mfma_f32_16x16x32_bf16 v[104:107], v[176:179], v[204:207], v[104:107]
	v_mfma_f32_16x16x32_bf16 v[100:103], v[184:187], v[204:207], v[100:103]
	v_mfma_f32_16x16x32_bf16 v[88:91], v[176:179], v[218:221], v[88:91]
	v_mfma_f32_16x16x32_bf16 v[84:87], v[184:187], v[218:221], v[84:87]
	v_mfma_f32_16x16x32_bf16 v[72:75], v[176:179], v[230:233], v[72:75]
	v_mfma_f32_16x16x32_bf16 v[68:71], v[184:187], v[230:233], v[68:71]
	s_setprio 0
	s_barrier
	s_add_i32 s34, s61, s40
	v_lshl_add_u64 v[188:189], v[188:189], 0, s[18:19]
	s_mov_b32 m0, s34
	ds_read_b128 v[192:195], v154 offset:49152
	ds_read_b128 v[196:199], v154 offset:50176
	ds_read_b128 v[200:203], v154 offset:51200
	ds_read_b128 v[204:207], v154 offset:52224
	ds_read_b128 v[208:211], v154 offset:53248
	ds_read_b128 v[218:221], v154 offset:54272
	ds_read_b128 v[226:229], v154 offset:55296
	ds_read_b128 v[230:233], v154 offset:56320
	global_load_lds_dwordx4 v[188:189], off
	s_add_i32 m0, s34, 0x2000
	s_add_u32 s30, s30, 0x40080
	v_lshl_add_u64 v[188:189], v[234:235], 0, s[18:19]
	s_addc_u32 s31, s31, 0
	s_add_i32 s34, s64, s40
	global_load_lds_dwordx4 v[188:189], off
	v_lshl_add_u64 v[188:189], s[30:31], 0, v[134:135]
	s_mov_b32 m0, s34
	s_nop 0
	global_load_lds_dwordx4 v[188:189], off
	v_lshl_add_u64 v[188:189], s[30:31], 0, v[138:139]
	s_add_i32 m0, s34, 0x2000
	s_nop 0
	global_load_lds_dwordx4 v[188:189], off
	v_lshl_add_u64 v[188:189], v[236:237], 0, s[18:19]
	s_mov_b32 m0, s44
	s_nop 0
	global_load_lds_dwordx4 v[188:189], off
	v_lshl_add_u64 v[188:189], v[238:239], 0, s[18:19]
	s_mov_b32 m0, s45
	s_nop 0
	global_load_lds_dwordx4 v[188:189], off
	s_waitcnt vmcnt(8)
	s_waitcnt lgkmcnt(0)
	v_mfma_f32_16x16x32_bf16 v[64:67], v[156:159], v[192:195], v[64:67]
	v_mfma_f32_16x16x32_bf16 v[60:63], v[164:167], v[192:195], v[60:63]
	v_mfma_f32_16x16x32_bf16 v[48:51], v[156:159], v[200:203], v[48:51]
	v_mfma_f32_16x16x32_bf16 v[44:47], v[164:167], v[200:203], v[44:47]
	s_barrier
	s_setprio 1
	s_waitcnt lgkmcnt(0)
	v_mfma_f32_16x16x32_bf16 v[32:35], v[156:159], v[208:211], v[32:35]
	v_mfma_f32_16x16x32_bf16 v[28:31], v[164:167], v[208:211], v[28:31]
	v_mfma_f32_16x16x32_bf16 v[16:19], v[156:159], v[226:229], v[16:19]
	v_mfma_f32_16x16x32_bf16 v[12:15], v[164:167], v[226:229], v[12:15]
	v_mfma_f32_16x16x32_bf16 v[64:67], v[160:163], v[196:199], v[64:67]
	v_mfma_f32_16x16x32_bf16 v[60:63], v[168:171], v[196:199], v[60:63]
	v_mfma_f32_16x16x32_bf16 v[48:51], v[160:163], v[204:207], v[48:51]
	v_mfma_f32_16x16x32_bf16 v[44:47], v[168:171], v[204:207], v[44:47]
	v_mfma_f32_16x16x32_bf16 v[32:35], v[160:163], v[218:221], v[32:35]
	v_mfma_f32_16x16x32_bf16 v[28:31], v[168:171], v[218:221], v[28:31]
	v_mfma_f32_16x16x32_bf16 v[16:19], v[160:163], v[230:233], v[16:19]
	v_mfma_f32_16x16x32_bf16 v[12:15], v[168:171], v[230:233], v[12:15]
	v_mfma_f32_16x16x32_bf16 v[56:59], v[172:175], v[192:195], v[56:59]
	v_mfma_f32_16x16x32_bf16 v[52:55], v[180:183], v[192:195], v[52:55]
	v_mfma_f32_16x16x32_bf16 v[40:43], v[172:175], v[200:203], v[40:43]
	v_mfma_f32_16x16x32_bf16 v[36:39], v[180:183], v[200:203], v[36:39]
	v_mfma_f32_16x16x32_bf16 v[24:27], v[172:175], v[208:211], v[24:27]
	v_mfma_f32_16x16x32_bf16 v[20:23], v[180:183], v[208:211], v[20:23]
	v_mfma_f32_16x16x32_bf16 v[8:11], v[172:175], v[226:229], v[8:11]
	v_mfma_f32_16x16x32_bf16 v[4:7], v[180:183], v[226:229], v[4:7]
	v_mfma_f32_16x16x32_bf16 v[56:59], v[176:179], v[196:199], v[56:59]
	v_mfma_f32_16x16x32_bf16 v[52:55], v[184:187], v[196:199], v[52:55]
	v_mfma_f32_16x16x32_bf16 v[40:43], v[176:179], v[204:207], v[40:43]
	v_mfma_f32_16x16x32_bf16 v[36:39], v[184:187], v[204:207], v[36:39]
	v_mfma_f32_16x16x32_bf16 v[24:27], v[176:179], v[218:221], v[24:27]
	v_mfma_f32_16x16x32_bf16 v[20:23], v[184:187], v[218:221], v[20:23]
	v_mfma_f32_16x16x32_bf16 v[8:11], v[176:179], v[230:233], v[8:11]
	v_mfma_f32_16x16x32_bf16 v[4:7], v[184:187], v[230:233], v[4:7]
	s_setprio 0
	s_barrier
	s_add_i32 s60, s60, 2
	s_add_u32 s28, s28, 0x100
	s_addc_u32 s29, s29, 0
	s_cmp_gt_u32 s60, 13
	s_cbranch_scc0 .LBB0_679
	s_add_u32 s28, s50, 0xffffff00
	s_addc_u32 s29, s51, -1
	s_andn2_b64 vcc, exec, s[4:5]
	s_cbranch_vccnz .LBB0_670
	v_mov_b32_e32 v4, 0
	s_mov_b32 s6, s20
	s_mov_b32 s12, s22
	s_mov_b64 s[16:17], s[26:27]
	s_mov_b32 s46, s49
	v_mov_b32_e32 v5, v4
	v_mov_b32_e32 v6, v4
	v_mov_b32_e32 v7, v4
	v_mov_b32_e32 v8, v4
	v_mov_b32_e32 v9, v4
	v_mov_b32_e32 v10, v4
	v_mov_b32_e32 v11, v4
	v_mov_b32_e32 v20, v4
	v_mov_b32_e32 v21, v4
	v_mov_b32_e32 v22, v4
	v_mov_b32_e32 v23, v4
	v_mov_b32_e32 v24, v4
	v_mov_b32_e32 v25, v4
	v_mov_b32_e32 v26, v4
	v_mov_b32_e32 v27, v4
	v_mov_b32_e32 v36, v4
	v_mov_b32_e32 v37, v4
	v_mov_b32_e32 v38, v4
	v_mov_b32_e32 v39, v4
	v_mov_b32_e32 v40, v4
	v_mov_b32_e32 v41, v4
	v_mov_b32_e32 v42, v4
	v_mov_b32_e32 v43, v4
	v_mov_b32_e32 v52, v4
	v_mov_b32_e32 v53, v4
	v_mov_b32_e32 v54, v4
	v_mov_b32_e32 v55, v4
	v_mov_b32_e32 v56, v4
	v_mov_b32_e32 v57, v4
	v_mov_b32_e32 v58, v4
	v_mov_b32_e32 v59, v4
	v_mov_b32_e32 v12, v4
	v_mov_b32_e32 v13, v4
	v_mov_b32_e32 v14, v4
	v_mov_b32_e32 v15, v4
	v_mov_b32_e32 v16, v4
	v_mov_b32_e32 v17, v4
	v_mov_b32_e32 v18, v4
	v_mov_b32_e32 v19, v4
	v_mov_b32_e32 v28, v4
	v_mov_b32_e32 v29, v4
	v_mov_b32_e32 v30, v4
	v_mov_b32_e32 v31, v4
	v_mov_b32_e32 v32, v4
	v_mov_b32_e32 v33, v4
	v_mov_b32_e32 v34, v4
	v_mov_b32_e32 v35, v4
	v_mov_b32_e32 v44, v4
	v_mov_b32_e32 v45, v4
	v_mov_b32_e32 v46, v4
	v_mov_b32_e32 v47, v4
	v_mov_b32_e32 v48, v4
	v_mov_b32_e32 v49, v4
	v_mov_b32_e32 v50, v4
	v_mov_b32_e32 v51, v4
	v_mov_b32_e32 v60, v4
	v_mov_b32_e32 v61, v4
	v_mov_b32_e32 v62, v4
	v_mov_b32_e32 v63, v4
	v_mov_b32_e32 v64, v4
	v_mov_b32_e32 v65, v4
	v_mov_b32_e32 v66, v4
	v_mov_b32_e32 v67, v4
	v_mov_b32_e32 v68, v4
	v_mov_b32_e32 v69, v4
	v_mov_b32_e32 v70, v4
	v_mov_b32_e32 v71, v4
	v_mov_b32_e32 v72, v4
	v_mov_b32_e32 v73, v4
	v_mov_b32_e32 v74, v4
	v_mov_b32_e32 v75, v4
	v_mov_b32_e32 v84, v4
	v_mov_b32_e32 v85, v4
	v_mov_b32_e32 v86, v4
	v_mov_b32_e32 v87, v4
	v_mov_b32_e32 v88, v4
	v_mov_b32_e32 v89, v4
	v_mov_b32_e32 v90, v4
	v_mov_b32_e32 v91, v4
	v_mov_b32_e32 v100, v4
	v_mov_b32_e32 v101, v4
	v_mov_b32_e32 v102, v4
	v_mov_b32_e32 v103, v4
	v_mov_b32_e32 v104, v4
	v_mov_b32_e32 v105, v4
	v_mov_b32_e32 v106, v4
	v_mov_b32_e32 v107, v4
	v_mov_b32_e32 v116, v4
	v_mov_b32_e32 v117, v4
	v_mov_b32_e32 v118, v4
	v_mov_b32_e32 v119, v4
	v_mov_b32_e32 v120, v4
	v_mov_b32_e32 v121, v4
	v_mov_b32_e32 v122, v4
	v_mov_b32_e32 v123, v4
	v_mov_b32_e32 v76, v4
	v_mov_b32_e32 v77, v4
	v_mov_b32_e32 v78, v4
	v_mov_b32_e32 v79, v4
	v_mov_b32_e32 v80, v4
	v_mov_b32_e32 v81, v4
	v_mov_b32_e32 v82, v4
	v_mov_b32_e32 v83, v4
	v_mov_b32_e32 v92, v4
	v_mov_b32_e32 v93, v4
	v_mov_b32_e32 v94, v4
	v_mov_b32_e32 v95, v4
	v_mov_b32_e32 v96, v4
	v_mov_b32_e32 v97, v4
	v_mov_b32_e32 v98, v4
	v_mov_b32_e32 v99, v4
	v_mov_b32_e32 v108, v4
	v_mov_b32_e32 v109, v4
	v_mov_b32_e32 v110, v4
	v_mov_b32_e32 v111, v4
	v_mov_b32_e32 v112, v4
	v_mov_b32_e32 v113, v4
	v_mov_b32_e32 v114, v4
	v_mov_b32_e32 v115, v4
	v_mov_b32_e32 v124, v4
	v_mov_b32_e32 v125, v4
	v_mov_b32_e32 v126, v4
	v_mov_b32_e32 v127, v4
	v_mov_b32_e32 v128, v4
	v_mov_b32_e32 v129, v4
	v_mov_b32_e32 v130, v4
	v_mov_b32_e32 v131, v4
	s_andn2_b64 vcc, exec, s[0:1]
	s_cbranch_vccnz .LBB0_671

.LBB0_820:
	ds_read_b128 v[148:151], v158
	ds_read_b128 v[162:165], v158 offset:1024
	ds_read_b128 v[166:169], v158 offset:2048
	ds_read_b128 v[170:173], v158 offset:3072
	ds_read_b128 v[174:177], v159
	ds_read_b128 v[178:181], v159 offset:1024
	ds_read_b128 v[182:185], v159 offset:2048
	ds_read_b128 v[186:189], v159 offset:3072
	s_add_u32 s40, s38, 0xfffc0080
	s_addc_u32 s41, s39, -1
	s_cmp_eq_u32 s71, 12
	s_cselect_b32 s43, s29, s41
	s_cselect_b32 s42, s67, s40
	s_cselect_b32 s41, s27, s70
	s_cselect_b32 s40, s68, s69
	v_lshl_add_u64 v[152:153], s[38:39], 0, v[140:141]
	s_add_i32 m0, s37, 0xc000
	ds_read_b128 v[190:193], v160
	ds_read_b128 v[194:197], v160 offset:1024
	ds_read_b128 v[198:201], v160 offset:2048
	ds_read_b128 v[202:205], v160 offset:3072
	ds_read_b128 v[206:209], v160 offset:4096
	ds_read_b128 v[218:221], v160 offset:5120
	ds_read_b128 v[226:229], v160 offset:6144
	ds_read_b128 v[230:233], v160 offset:7168
	global_load_lds_dwordx4 v[152:153], off
	v_lshl_add_u64 v[152:153], s[38:39], 0, v[142:143]
	s_add_i32 m0, s37, 0xe000
	s_nop 0
	global_load_lds_dwordx4 v[152:153], off
	s_waitcnt vmcnt(8)
	s_waitcnt lgkmcnt(0)
	v_mfma_f32_16x16x32_bf16 v[128:131], v[148:151], v[190:193], v[128:131]
	v_mfma_f32_16x16x32_bf16 v[124:127], v[166:169], v[190:193], v[124:127]
	v_mfma_f32_16x16x32_bf16 v[112:115], v[148:151], v[198:201], v[112:115]
	v_mfma_f32_16x16x32_bf16 v[108:111], v[166:169], v[198:201], v[108:111]
	s_barrier
	s_setprio 1
	s_waitcnt lgkmcnt(0)
	v_mfma_f32_16x16x32_bf16 v[96:99], v[148:151], v[206:209], v[96:99]
	v_mfma_f32_16x16x32_bf16 v[92:95], v[166:169], v[206:209], v[92:95]
	v_mfma_f32_16x16x32_bf16 v[80:83], v[148:151], v[226:229], v[80:83]
	v_mfma_f32_16x16x32_bf16 v[76:79], v[166:169], v[226:229], v[76:79]
	v_mfma_f32_16x16x32_bf16 v[128:131], v[162:165], v[194:197], v[128:131]
	v_mfma_f32_16x16x32_bf16 v[124:127], v[170:173], v[194:197], v[124:127]
	v_mfma_f32_16x16x32_bf16 v[112:115], v[162:165], v[202:205], v[112:115]
	v_mfma_f32_16x16x32_bf16 v[108:111], v[170:173], v[202:205], v[108:111]
	v_mfma_f32_16x16x32_bf16 v[96:99], v[162:165], v[218:221], v[96:99]
	v_mfma_f32_16x16x32_bf16 v[92:95], v[170:173], v[218:221], v[92:95]
	v_mfma_f32_16x16x32_bf16 v[80:83], v[162:165], v[230:233], v[80:83]
	v_mfma_f32_16x16x32_bf16 v[76:79], v[170:173], v[230:233], v[76:79]
	v_mfma_f32_16x16x32_bf16 v[120:123], v[174:177], v[190:193], v[120:123]
	v_mfma_f32_16x16x32_bf16 v[116:119], v[182:185], v[190:193], v[116:119]
	v_mfma_f32_16x16x32_bf16 v[104:107], v[174:177], v[198:201], v[104:107]
	v_mfma_f32_16x16x32_bf16 v[100:103], v[182:185], v[198:201], v[100:103]
	v_mfma_f32_16x16x32_bf16 v[88:91], v[174:177], v[206:209], v[88:91]
	v_mfma_f32_16x16x32_bf16 v[84:87], v[182:185], v[206:209], v[84:87]
	v_mfma_f32_16x16x32_bf16 v[72:75], v[174:177], v[226:229], v[72:75]
	v_mfma_f32_16x16x32_bf16 v[68:71], v[182:185], v[226:229], v[68:71]
	v_mfma_f32_16x16x32_bf16 v[120:123], v[178:181], v[194:197], v[120:123]
	v_mfma_f32_16x16x32_bf16 v[116:119], v[186:189], v[194:197], v[116:119]
	v_mfma_f32_16x16x32_bf16 v[104:107], v[178:181], v[202:205], v[104:107]
	v_mfma_f32_16x16x32_bf16 v[100:103], v[186:189], v[202:205], v[100:103]
	v_mfma_f32_16x16x32_bf16 v[88:91], v[178:181], v[218:221], v[88:91]
	v_mfma_f32_16x16x32_bf16 v[84:87], v[186:189], v[218:221], v[84:87]
	v_mfma_f32_16x16x32_bf16 v[72:75], v[178:181], v[230:233], v[72:75]
	v_mfma_f32_16x16x32_bf16 v[68:71], v[186:189], v[230:233], v[68:71]
	s_setprio 0
	s_barrier
	s_add_i32 s72, s58, s33
	v_lshl_add_u64 v[152:153], s[40:41], 0, v[134:135]
	s_mov_b32 m0, s72
	ds_read_b128 v[190:193], v160 offset:16384
	ds_read_b128 v[194:197], v160 offset:17408
	ds_read_b128 v[198:201], v160 offset:18432
	ds_read_b128 v[202:205], v160 offset:19456
	ds_read_b128 v[206:209], v160 offset:20480
	ds_read_b128 v[218:221], v160 offset:21504
	ds_read_b128 v[226:229], v160 offset:22528
	ds_read_b128 v[230:233], v160 offset:23552
	global_load_lds_dwordx4 v[152:153], off
	s_add_i32 m0, s72, 0x2000
	s_add_u32 s72, s40, 0x40000
	v_lshl_add_u64 v[210:211], s[40:41], 0, v[138:139]
	s_addc_u32 s73, s41, 0
	s_add_i32 s74, s59, s33
	global_load_lds_dwordx4 v[210:211], off
	v_lshl_add_u64 v[234:235], s[72:73], 0, v[134:135]
	s_mov_b32 m0, s74
	v_lshl_add_u64 v[236:237], s[42:43], 0, v[136:137]
	global_load_lds_dwordx4 v[234:235], off
	v_lshl_add_u64 v[234:235], s[72:73], 0, v[138:139]
	s_add_i32 m0, s74, 0x2000
	s_nop 0
	global_load_lds_dwordx4 v[234:235], off
	v_lshl_add_u64 v[234:235], s[42:43], 0, v[132:133]
	s_mov_b32 m0, s37
	s_nop 0
	global_load_lds_dwordx4 v[234:235], off
	s_mov_b32 m0, s44
	s_nop 0
	global_load_lds_dwordx4 v[236:237], off
	s_waitcnt vmcnt(8)
	s_waitcnt lgkmcnt(0)
	v_mfma_f32_16x16x32_bf16 v[64:67], v[148:151], v[190:193], v[64:67]
	v_mfma_f32_16x16x32_bf16 v[60:63], v[166:169], v[190:193], v[60:63]
	v_mfma_f32_16x16x32_bf16 v[48:51], v[148:151], v[198:201], v[48:51]
	v_mfma_f32_16x16x32_bf16 v[44:47], v[166:169], v[198:201], v[44:47]
	s_barrier
	s_setprio 1
	s_waitcnt lgkmcnt(0)
	v_mfma_f32_16x16x32_bf16 v[32:35], v[148:151], v[206:209], v[32:35]
	v_mfma_f32_16x16x32_bf16 v[28:31], v[166:169], v[206:209], v[28:31]
	v_mfma_f32_16x16x32_bf16 v[16:19], v[148:151], v[226:229], v[16:19]
	v_mfma_f32_16x16x32_bf16 v[12:15], v[166:169], v[226:229], v[12:15]
	v_mfma_f32_16x16x32_bf16 v[64:67], v[162:165], v[194:197], v[64:67]
	v_mfma_f32_16x16x32_bf16 v[60:63], v[170:173], v[194:197], v[60:63]
	v_mfma_f32_16x16x32_bf16 v[48:51], v[162:165], v[202:205], v[48:51]
	v_mfma_f32_16x16x32_bf16 v[44:47], v[170:173], v[202:205], v[44:47]
	v_mfma_f32_16x16x32_bf16 v[32:35], v[162:165], v[218:221], v[32:35]
	v_mfma_f32_16x16x32_bf16 v[28:31], v[170:173], v[218:221], v[28:31]
	v_mfma_f32_16x16x32_bf16 v[16:19], v[162:165], v[230:233], v[16:19]
	v_mfma_f32_16x16x32_bf16 v[12:15], v[170:173], v[230:233], v[12:15]
	v_mfma_f32_16x16x32_bf16 v[56:59], v[174:177], v[190:193], v[56:59]
	v_mfma_f32_16x16x32_bf16 v[52:55], v[182:185], v[190:193], v[52:55]
	v_mfma_f32_16x16x32_bf16 v[40:43], v[174:177], v[198:201], v[40:43]
	v_mfma_f32_16x16x32_bf16 v[36:39], v[182:185], v[198:201], v[36:39]
	v_mfma_f32_16x16x32_bf16 v[24:27], v[174:177], v[206:209], v[24:27]
	v_mfma_f32_16x16x32_bf16 v[20:23], v[182:185], v[206:209], v[20:23]
	v_mfma_f32_16x16x32_bf16 v[8:11], v[174:177], v[226:229], v[8:11]
	v_mfma_f32_16x16x32_bf16 v[4:7], v[182:185], v[226:229], v[4:7]
	v_mfma_f32_16x16x32_bf16 v[56:59], v[178:181], v[194:197], v[56:59]
	v_mfma_f32_16x16x32_bf16 v[52:55], v[186:189], v[194:197], v[52:55]
	v_mfma_f32_16x16x32_bf16 v[40:43], v[178:181], v[202:205], v[40:43]
	v_mfma_f32_16x16x32_bf16 v[36:39], v[186:189], v[202:205], v[36:39]
	v_mfma_f32_16x16x32_bf16 v[24:27], v[178:181], v[218:221], v[24:27]
	v_mfma_f32_16x16x32_bf16 v[20:23], v[186:189], v[218:221], v[20:23]
	v_mfma_f32_16x16x32_bf16 v[8:11], v[178:181], v[230:233], v[8:11]
	v_mfma_f32_16x16x32_bf16 v[4:7], v[186:189], v[230:233], v[4:7]
	s_setprio 0
	s_barrier
	s_add_i32 s72, 0, 0x18000
	v_add_u32_e32 v161, s72, v154
	s_add_i32 s73, 0, 0x1c000
	ds_read_b128 v[148:151], v161
	ds_read_b128 v[162:165], v161 offset:1024
	ds_read_b128 v[166:169], v161 offset:2048
	ds_read_b128 v[170:173], v161 offset:3072
	v_add_u32_e32 v161, s73, v154
	ds_read_b128 v[174:177], v161
	ds_read_b128 v[178:181], v161 offset:1024
	ds_read_b128 v[182:185], v161 offset:2048
	ds_read_b128 v[186:189], v161 offset:3072
	s_add_u32 s42, s42, 0x40000
	s_addc_u32 s43, s43, 0
	s_mov_b32 m0, s45
	v_lshl_add_u64 v[238:239], s[42:43], 0, v[132:133]
	ds_read_b128 v[190:193], v160 offset:32768
	ds_read_b128 v[194:197], v160 offset:33792
	ds_read_b128 v[198:201], v160 offset:34816
	ds_read_b128 v[202:205], v160 offset:35840
	ds_read_b128 v[206:209], v160 offset:36864
	ds_read_b128 v[218:221], v160 offset:37888
	ds_read_b128 v[226:229], v160 offset:38912
	ds_read_b128 v[230:233], v160 offset:39936
	global_load_lds_dwordx4 v[238:239], off
	v_lshl_add_u64 v[238:239], s[42:43], 0, v[136:137]
	s_mov_b32 m0, s46
	s_nop 0
	global_load_lds_dwordx4 v[238:239], off
	s_waitcnt vmcnt(8)
	s_waitcnt lgkmcnt(0)
	v_mfma_f32_16x16x32_bf16 v[128:131], v[148:151], v[190:193], v[128:131]
	v_mfma_f32_16x16x32_bf16 v[124:127], v[166:169], v[190:193], v[124:127]
	v_mfma_f32_16x16x32_bf16 v[112:115], v[148:151], v[198:201], v[112:115]
	v_mfma_f32_16x16x32_bf16 v[108:111], v[166:169], v[198:201], v[108:111]
	s_barrier
	s_setprio 1
	s_waitcnt lgkmcnt(0)
	v_mfma_f32_16x16x32_bf16 v[96:99], v[148:151], v[206:209], v[96:99]
	v_mfma_f32_16x16x32_bf16 v[92:95], v[166:169], v[206:209], v[92:95]
	v_mfma_f32_16x16x32_bf16 v[80:83], v[148:151], v[226:229], v[80:83]
	v_mfma_f32_16x16x32_bf16 v[76:79], v[166:169], v[226:229], v[76:79]
	v_mfma_f32_16x16x32_bf16 v[128:131], v[162:165], v[194:197], v[128:131]
	v_mfma_f32_16x16x32_bf16 v[124:127], v[170:173], v[194:197], v[124:127]
	v_mfma_f32_16x16x32_bf16 v[112:115], v[162:165], v[202:205], v[112:115]
	v_mfma_f32_16x16x32_bf16 v[108:111], v[170:173], v[202:205], v[108:111]
	v_mfma_f32_16x16x32_bf16 v[96:99], v[162:165], v[218:221], v[96:99]
	v_mfma_f32_16x16x32_bf16 v[92:95], v[170:173], v[218:221], v[92:95]
	v_mfma_f32_16x16x32_bf16 v[80:83], v[162:165], v[230:233], v[80:83]
	v_mfma_f32_16x16x32_bf16 v[76:79], v[170:173], v[230:233], v[76:79]
	v_mfma_f32_16x16x32_bf16 v[120:123], v[174:177], v[190:193], v[120:123]
	v_mfma_f32_16x16x32_bf16 v[116:119], v[182:185], v[190:193], v[116:119]
	v_mfma_f32_16x16x32_bf16 v[104:107], v[174:177], v[198:201], v[104:107]
	v_mfma_f32_16x16x32_bf16 v[100:103], v[182:185], v[198:201], v[100:103]
	v_mfma_f32_16x16x32_bf16 v[88:91], v[174:177], v[206:209], v[88:91]
	v_mfma_f32_16x16x32_bf16 v[84:87], v[182:185], v[206:209], v[84:87]
	v_mfma_f32_16x16x32_bf16 v[72:75], v[174:177], v[226:229], v[72:75]
	v_mfma_f32_16x16x32_bf16 v[68:71], v[182:185], v[226:229], v[68:71]
	v_mfma_f32_16x16x32_bf16 v[120:123], v[178:181], v[194:197], v[120:123]
	v_mfma_f32_16x16x32_bf16 v[116:119], v[186:189], v[194:197], v[116:119]
	v_mfma_f32_16x16x32_bf16 v[104:107], v[178:181], v[202:205], v[104:107]
	v_mfma_f32_16x16x32_bf16 v[100:103], v[186:189], v[202:205], v[100:103]
	v_mfma_f32_16x16x32_bf16 v[88:91], v[178:181], v[218:221], v[88:91]
	v_mfma_f32_16x16x32_bf16 v[84:87], v[186:189], v[218:221], v[84:87]
	v_mfma_f32_16x16x32_bf16 v[72:75], v[178:181], v[230:233], v[72:75]
	v_mfma_f32_16x16x32_bf16 v[68:71], v[186:189], v[230:233], v[68:71]
	s_setprio 0
	s_barrier
	s_add_i32 s42, s72, s33
	v_lshl_add_u64 v[152:153], v[152:153], 0, s[12:13]
	s_mov_b32 m0, s42
	ds_read_b128 v[190:193], v160 offset:49152
	ds_read_b128 v[194:197], v160 offset:50176
	ds_read_b128 v[198:201], v160 offset:51200
	ds_read_b128 v[202:205], v160 offset:52224
	ds_read_b128 v[206:209], v160 offset:53248
	ds_read_b128 v[218:221], v160 offset:54272
	ds_read_b128 v[226:229], v160 offset:55296
	ds_read_b128 v[230:233], v160 offset:56320
	global_load_lds_dwordx4 v[152:153], off
	s_add_i32 m0, s42, 0x2000
	s_add_u32 s40, s40, 0x40080
	v_lshl_add_u64 v[152:153], v[210:211], 0, s[12:13]
	s_addc_u32 s41, s41, 0
	s_add_i32 s42, s73, s33
	global_load_lds_dwordx4 v[152:153], off
	v_lshl_add_u64 v[152:153], s[40:41], 0, v[134:135]
	s_mov_b32 m0, s42
	s_nop 0
	global_load_lds_dwordx4 v[152:153], off
	v_lshl_add_u64 v[152:153], s[40:41], 0, v[138:139]
	s_add_i32 m0, s42, 0x2000
	s_nop 0
	global_load_lds_dwordx4 v[152:153], off
	v_lshl_add_u64 v[152:153], v[234:235], 0, s[12:13]
	s_mov_b32 m0, s48
	s_nop 0
	global_load_lds_dwordx4 v[152:153], off
	v_lshl_add_u64 v[152:153], v[236:237], 0, s[12:13]
	s_mov_b32 m0, s49
	s_nop 0
	global_load_lds_dwordx4 v[152:153], off
	s_waitcnt vmcnt(8)
	s_waitcnt lgkmcnt(0)
	v_mfma_f32_16x16x32_bf16 v[64:67], v[148:151], v[190:193], v[64:67]
	v_mfma_f32_16x16x32_bf16 v[60:63], v[166:169], v[190:193], v[60:63]
	v_mfma_f32_16x16x32_bf16 v[48:51], v[148:151], v[198:201], v[48:51]
	v_mfma_f32_16x16x32_bf16 v[44:47], v[166:169], v[198:201], v[44:47]
	s_barrier
	s_setprio 1
	s_waitcnt lgkmcnt(0)
	v_mfma_f32_16x16x32_bf16 v[32:35], v[148:151], v[206:209], v[32:35]
	v_mfma_f32_16x16x32_bf16 v[28:31], v[166:169], v[206:209], v[28:31]
	v_mfma_f32_16x16x32_bf16 v[16:19], v[148:151], v[226:229], v[16:19]
	v_mfma_f32_16x16x32_bf16 v[12:15], v[166:169], v[226:229], v[12:15]
	v_mfma_f32_16x16x32_bf16 v[64:67], v[162:165], v[194:197], v[64:67]
	v_mfma_f32_16x16x32_bf16 v[60:63], v[170:173], v[194:197], v[60:63]
	v_mfma_f32_16x16x32_bf16 v[48:51], v[162:165], v[202:205], v[48:51]
	v_mfma_f32_16x16x32_bf16 v[44:47], v[170:173], v[202:205], v[44:47]
	v_mfma_f32_16x16x32_bf16 v[32:35], v[162:165], v[218:221], v[32:35]
	v_mfma_f32_16x16x32_bf16 v[28:31], v[170:173], v[218:221], v[28:31]
	v_mfma_f32_16x16x32_bf16 v[16:19], v[162:165], v[230:233], v[16:19]
	v_mfma_f32_16x16x32_bf16 v[12:15], v[170:173], v[230:233], v[12:15]
	v_mfma_f32_16x16x32_bf16 v[56:59], v[174:177], v[190:193], v[56:59]
	v_mfma_f32_16x16x32_bf16 v[52:55], v[182:185], v[190:193], v[52:55]
	v_mfma_f32_16x16x32_bf16 v[40:43], v[174:177], v[198:201], v[40:43]
	v_mfma_f32_16x16x32_bf16 v[36:39], v[182:185], v[198:201], v[36:39]
	v_mfma_f32_16x16x32_bf16 v[24:27], v[174:177], v[206:209], v[24:27]
	v_mfma_f32_16x16x32_bf16 v[20:23], v[182:185], v[206:209], v[20:23]
	v_mfma_f32_16x16x32_bf16 v[8:11], v[174:177], v[226:229], v[8:11]
	v_mfma_f32_16x16x32_bf16 v[4:7], v[182:185], v[226:229], v[4:7]
	v_mfma_f32_16x16x32_bf16 v[56:59], v[178:181], v[194:197], v[56:59]
	v_mfma_f32_16x16x32_bf16 v[52:55], v[186:189], v[194:197], v[52:55]
	v_mfma_f32_16x16x32_bf16 v[40:43], v[178:181], v[202:205], v[40:43]
	v_mfma_f32_16x16x32_bf16 v[36:39], v[186:189], v[202:205], v[36:39]
	v_mfma_f32_16x16x32_bf16 v[24:27], v[178:181], v[218:221], v[24:27]
	v_mfma_f32_16x16x32_bf16 v[20:23], v[186:189], v[218:221], v[20:23]
	v_mfma_f32_16x16x32_bf16 v[8:11], v[178:181], v[230:233], v[8:11]
	v_mfma_f32_16x16x32_bf16 v[4:7], v[186:189], v[230:233], v[4:7]
	s_setprio 0
	s_barrier
	s_add_i32 s71, s71, 2
	s_add_u32 s38, s38, 0x100
	s_addc_u32 s39, s39, 0
	s_add_u32 s69, s69, 0x100
	s_addc_u32 s70, s70, 0
	s_cmp_gt_u32 s71, 13
	s_cbranch_scc0 .LBB0_820
	s_and_b64 vcc, exec, s[16:17]
	s_cbranch_vccz .LBB0_823
	s_barrier

.LBB0_936:
	v_add_u32_e32 v93, s51, v152
	ds_read_b128 v[154:157], v93
	ds_read_b128 v[158:161], v93 offset:1024
	ds_read_b128 v[166:169], v93 offset:2048
	ds_read_b128 v[170:173], v93 offset:3072
	v_add_u32_e32 v93, s58, v152
	ds_read_b128 v[174:177], v93
	ds_read_b128 v[178:181], v93 offset:1024
	ds_read_b128 v[182:185], v93 offset:2048
	ds_read_b128 v[186:189], v93 offset:3072
	s_add_i32 s67, s34, 2
	s_add_u32 s68, s30, 0x80
	s_addc_u32 s35, s31, 0
	s_cmp_eq_u32 s50, s34
	s_cselect_b32 s34, s6, s68
	s_cselect_b32 s35, s7, s35
	s_cselect_b32 s69, s29, s66
	s_cselect_b32 s68, s28, s65
	v_lshl_add_u64 v[94:95], s[30:31], 0, v[120:121]
	s_add_i32 m0, s42, 0xc000
	ds_read_b128 v[190:193], v153
	ds_read_b128 v[194:197], v153 offset:1024
	ds_read_b128 v[198:201], v153 offset:2048
	ds_read_b128 v[202:205], v153 offset:3072
	ds_read_b128 v[206:209], v153 offset:4096
	ds_read_b128 v[218:221], v153 offset:5120
	ds_read_b128 v[226:229], v153 offset:6144
	ds_read_b128 v[230:233], v153 offset:7168
	global_load_lds_dwordx4 v[94:95], off
	v_lshl_add_u64 v[94:95], s[30:31], 0, v[122:123]
	s_add_i32 m0, s42, 0xe000
	s_nop 0
	global_load_lds_dwordx4 v[94:95], off
	s_waitcnt vmcnt(8)
	s_waitcnt lgkmcnt(0)
	v_mfma_f32_16x16x32_bf16 v[148:151], v[154:157], v[190:193], v[148:151]
	v_mfma_f32_16x16x32_bf16 v[144:147], v[166:169], v[190:193], v[144:147]
	v_mfma_f32_16x16x32_bf16 v[128:131], v[154:157], v[198:201], v[128:131]
	v_mfma_f32_16x16x32_bf16 v[124:127], v[166:169], v[198:201], v[124:127]
	s_barrier
	s_setprio 1
	s_waitcnt lgkmcnt(0)
	v_mfma_f32_16x16x32_bf16 v[104:107], v[154:157], v[206:209], v[104:107]
	v_mfma_f32_16x16x32_bf16 v[94:97], v[166:169], v[206:209], v[96:99]
	v_mfma_f32_16x16x32_bf16 v[80:83], v[154:157], v[226:229], v[80:83]
	v_mfma_f32_16x16x32_bf16 v[76:79], v[166:169], v[226:229], v[76:79]
	v_mfma_f32_16x16x32_bf16 v[148:151], v[158:161], v[194:197], v[148:151]
	v_mfma_f32_16x16x32_bf16 v[144:147], v[170:173], v[194:197], v[144:147]
	v_mfma_f32_16x16x32_bf16 v[128:131], v[158:161], v[202:205], v[128:131]
	v_mfma_f32_16x16x32_bf16 v[124:127], v[170:173], v[202:205], v[124:127]
	v_mfma_f32_16x16x32_bf16 v[104:107], v[158:161], v[218:221], v[104:107]
	v_mfma_f32_16x16x32_bf16 v[94:97], v[170:173], v[218:221], v[94:97]
	v_mfma_f32_16x16x32_bf16 v[80:83], v[158:161], v[230:233], v[80:83]
	v_mfma_f32_16x16x32_bf16 v[76:79], v[170:173], v[230:233], v[76:79]
	v_mfma_f32_16x16x32_bf16 v[140:143], v[174:177], v[190:193], v[140:143]
	v_mfma_f32_16x16x32_bf16 v[136:139], v[182:185], v[190:193], v[136:139]
	v_mfma_f32_16x16x32_bf16 v[116:119], v[174:177], v[198:201], v[116:119]
	v_mfma_f32_16x16x32_bf16 v[108:111], v[182:185], v[198:201], v[108:111]
	v_mfma_f32_16x16x32_bf16 v[88:91], v[174:177], v[206:209], v[88:91]
	v_mfma_f32_16x16x32_bf16 v[84:87], v[182:185], v[206:209], v[84:87]
	v_mfma_f32_16x16x32_bf16 v[72:75], v[174:177], v[226:229], v[72:75]
	v_mfma_f32_16x16x32_bf16 v[68:71], v[182:185], v[226:229], v[68:71]
	v_mfma_f32_16x16x32_bf16 v[140:143], v[178:181], v[194:197], v[140:143]
	v_mfma_f32_16x16x32_bf16 v[136:139], v[186:189], v[194:197], v[136:139]
	v_mfma_f32_16x16x32_bf16 v[116:119], v[178:181], v[202:205], v[116:119]
	v_mfma_f32_16x16x32_bf16 v[108:111], v[186:189], v[202:205], v[108:111]
	v_mfma_f32_16x16x32_bf16 v[88:91], v[178:181], v[218:221], v[88:91]
	v_mfma_f32_16x16x32_bf16 v[84:87], v[186:189], v[218:221], v[84:87]
	v_mfma_f32_16x16x32_bf16 v[72:75], v[178:181], v[230:233], v[72:75]
	v_mfma_f32_16x16x32_bf16 v[68:71], v[186:189], v[230:233], v[68:71]
	s_setprio 0
	s_barrier
	s_add_i32 s70, s51, s38
	v_lshl_add_u64 v[162:163], s[68:69], 0, v[102:103]
	s_mov_b32 m0, s70
	ds_read_b128 v[190:193], v153 offset:16384
	ds_read_b128 v[194:197], v153 offset:17408
	ds_read_b128 v[198:201], v153 offset:18432
	ds_read_b128 v[202:205], v153 offset:19456
	ds_read_b128 v[206:209], v153 offset:20480
	ds_read_b128 v[218:221], v153 offset:21504
	ds_read_b128 v[226:229], v153 offset:22528
	ds_read_b128 v[230:233], v153 offset:23552
	global_load_lds_dwordx4 v[162:163], off
	s_add_i32 m0, s70, 0x2000
	v_lshl_add_u64 v[210:211], s[68:69], 0, v[114:115]
	s_add_u32 s68, s68, s16
	s_addc_u32 s69, s69, s17
	s_add_i32 s70, s58, s38
	global_load_lds_dwordx4 v[210:211], off
	v_lshl_add_u64 v[234:235], s[68:69], 0, v[102:103]
	s_mov_b32 m0, s70
	v_lshl_add_u64 v[236:237], s[68:69], 0, v[114:115]
	global_load_lds_dwordx4 v[234:235], off
	s_add_i32 m0, s70, 0x2000
	v_lshl_add_u64 v[238:239], s[34:35], 0, v[100:101]
	global_load_lds_dwordx4 v[236:237], off
	s_mov_b32 m0, s42
	v_lshl_add_u64 v[240:241], s[34:35], 0, v[112:113]
	global_load_lds_dwordx4 v[238:239], off
	s_mov_b32 m0, s43
	s_nop 0
	global_load_lds_dwordx4 v[240:241], off
	s_waitcnt vmcnt(8)
	s_waitcnt lgkmcnt(0)
	v_mfma_f32_16x16x32_bf16 v[64:67], v[154:157], v[190:193], v[64:67]
	v_mfma_f32_16x16x32_bf16 v[60:63], v[166:169], v[190:193], v[60:63]
	v_mfma_f32_16x16x32_bf16 v[48:51], v[154:157], v[198:201], v[48:51]
	v_mfma_f32_16x16x32_bf16 v[44:47], v[166:169], v[198:201], v[44:47]
	s_barrier
	s_setprio 1
	s_waitcnt lgkmcnt(0)
	v_mfma_f32_16x16x32_bf16 v[32:35], v[154:157], v[206:209], v[32:35]
	v_mfma_f32_16x16x32_bf16 v[28:31], v[166:169], v[206:209], v[28:31]
	v_mfma_f32_16x16x32_bf16 v[16:19], v[154:157], v[226:229], v[16:19]
	v_mfma_f32_16x16x32_bf16 v[12:15], v[166:169], v[226:229], v[12:15]
	v_mfma_f32_16x16x32_bf16 v[64:67], v[158:161], v[194:197], v[64:67]
	v_mfma_f32_16x16x32_bf16 v[60:63], v[170:173], v[194:197], v[60:63]
	v_mfma_f32_16x16x32_bf16 v[48:51], v[158:161], v[202:205], v[48:51]
	v_mfma_f32_16x16x32_bf16 v[44:47], v[170:173], v[202:205], v[44:47]
	v_mfma_f32_16x16x32_bf16 v[32:35], v[158:161], v[218:221], v[32:35]
	v_mfma_f32_16x16x32_bf16 v[28:31], v[170:173], v[218:221], v[28:31]
	v_mfma_f32_16x16x32_bf16 v[16:19], v[158:161], v[230:233], v[16:19]
	v_mfma_f32_16x16x32_bf16 v[12:15], v[170:173], v[230:233], v[12:15]
	v_mfma_f32_16x16x32_bf16 v[56:59], v[174:177], v[190:193], v[56:59]
	v_mfma_f32_16x16x32_bf16 v[52:55], v[182:185], v[190:193], v[52:55]
	v_mfma_f32_16x16x32_bf16 v[40:43], v[174:177], v[198:201], v[40:43]
	v_mfma_f32_16x16x32_bf16 v[36:39], v[182:185], v[198:201], v[36:39]
	v_mfma_f32_16x16x32_bf16 v[24:27], v[174:177], v[206:209], v[24:27]
	v_mfma_f32_16x16x32_bf16 v[20:23], v[182:185], v[206:209], v[20:23]
	v_mfma_f32_16x16x32_bf16 v[8:11], v[174:177], v[226:229], v[8:11]
	v_mfma_f32_16x16x32_bf16 v[4:7], v[182:185], v[226:229], v[4:7]
	v_mfma_f32_16x16x32_bf16 v[56:59], v[178:181], v[194:197], v[56:59]
	v_mfma_f32_16x16x32_bf16 v[52:55], v[186:189], v[194:197], v[52:55]
	v_mfma_f32_16x16x32_bf16 v[40:43], v[178:181], v[202:205], v[40:43]
	v_mfma_f32_16x16x32_bf16 v[36:39], v[186:189], v[202:205], v[36:39]
	v_mfma_f32_16x16x32_bf16 v[24:27], v[178:181], v[218:221], v[24:27]
	v_mfma_f32_16x16x32_bf16 v[20:23], v[186:189], v[218:221], v[20:23]
	v_mfma_f32_16x16x32_bf16 v[8:11], v[178:181], v[230:233], v[8:11]
	v_mfma_f32_16x16x32_bf16 v[4:7], v[186:189], v[230:233], v[4:7]
	s_setprio 0
	s_barrier
	s_add_i32 s68, 0, 0x18000
	v_add_u32_e32 v93, s68, v152
	s_add_i32 s69, 0, 0x1c000
	ds_read_b128 v[154:157], v93
	ds_read_b128 v[158:161], v93 offset:1024
	ds_read_b128 v[166:169], v93 offset:2048
	ds_read_b128 v[170:173], v93 offset:3072
	v_add_u32_e32 v93, s69, v152
	ds_read_b128 v[174:177], v93
	ds_read_b128 v[178:181], v93 offset:1024
	ds_read_b128 v[182:185], v93 offset:2048
	ds_read_b128 v[186:189], v93 offset:3072
	s_add_u32 s34, s34, s16
	s_addc_u32 s35, s35, s17
	s_mov_b32 m0, s44
	v_lshl_add_u64 v[98:99], s[34:35], 0, v[100:101]
	ds_read_b128 v[190:193], v153 offset:32768
	ds_read_b128 v[194:197], v153 offset:33792
	ds_read_b128 v[198:201], v153 offset:34816
	ds_read_b128 v[202:205], v153 offset:35840
	ds_read_b128 v[206:209], v153 offset:36864
	ds_read_b128 v[218:221], v153 offset:37888
	ds_read_b128 v[226:229], v153 offset:38912
	ds_read_b128 v[230:233], v153 offset:39936
	global_load_lds_dwordx4 v[98:99], off
	v_lshl_add_u64 v[98:99], s[34:35], 0, v[112:113]
	s_mov_b32 m0, s45
	s_nop 0
	global_load_lds_dwordx4 v[98:99], off
	s_waitcnt vmcnt(8)
	s_waitcnt lgkmcnt(0)
	v_mfma_f32_16x16x32_bf16 v[148:151], v[154:157], v[190:193], v[148:151]
	v_mfma_f32_16x16x32_bf16 v[144:147], v[166:169], v[190:193], v[144:147]
	v_mfma_f32_16x16x32_bf16 v[128:131], v[154:157], v[198:201], v[128:131]
	v_mfma_f32_16x16x32_bf16 v[124:127], v[166:169], v[198:201], v[124:127]
	s_barrier
	s_setprio 1
	s_waitcnt lgkmcnt(0)
	v_mfma_f32_16x16x32_bf16 v[104:107], v[154:157], v[206:209], v[104:107]
	v_mfma_f32_16x16x32_bf16 v[94:97], v[166:169], v[206:209], v[94:97]
	v_mfma_f32_16x16x32_bf16 v[80:83], v[154:157], v[226:229], v[80:83]
	v_mfma_f32_16x16x32_bf16 v[76:79], v[166:169], v[226:229], v[76:79]
	v_mfma_f32_16x16x32_bf16 v[148:151], v[158:161], v[194:197], v[148:151]
	v_mfma_f32_16x16x32_bf16 v[144:147], v[170:173], v[194:197], v[144:147]
	v_mfma_f32_16x16x32_bf16 v[128:131], v[158:161], v[202:205], v[128:131]
	v_mfma_f32_16x16x32_bf16 v[124:127], v[170:173], v[202:205], v[124:127]
	v_mfma_f32_16x16x32_bf16 v[104:107], v[158:161], v[218:221], v[104:107]
	v_mfma_f32_16x16x32_bf16 v[96:99], v[170:173], v[218:221], v[94:97]
	v_mfma_f32_16x16x32_bf16 v[80:83], v[158:161], v[230:233], v[80:83]
	v_mfma_f32_16x16x32_bf16 v[76:79], v[170:173], v[230:233], v[76:79]
	v_mfma_f32_16x16x32_bf16 v[140:143], v[174:177], v[190:193], v[140:143]
	v_mfma_f32_16x16x32_bf16 v[136:139], v[182:185], v[190:193], v[136:139]
	v_mfma_f32_16x16x32_bf16 v[116:119], v[174:177], v[198:201], v[116:119]
	v_mfma_f32_16x16x32_bf16 v[108:111], v[182:185], v[198:201], v[108:111]
	v_mfma_f32_16x16x32_bf16 v[88:91], v[174:177], v[206:209], v[88:91]
	v_mfma_f32_16x16x32_bf16 v[84:87], v[182:185], v[206:209], v[84:87]
	v_mfma_f32_16x16x32_bf16 v[72:75], v[174:177], v[226:229], v[72:75]
	v_mfma_f32_16x16x32_bf16 v[68:71], v[182:185], v[226:229], v[68:71]
	v_mfma_f32_16x16x32_bf16 v[140:143], v[178:181], v[194:197], v[140:143]
	v_mfma_f32_16x16x32_bf16 v[136:139], v[186:189], v[194:197], v[136:139]
	v_mfma_f32_16x16x32_bf16 v[116:119], v[178:181], v[202:205], v[116:119]
	v_mfma_f32_16x16x32_bf16 v[108:111], v[186:189], v[202:205], v[108:111]
	v_mfma_f32_16x16x32_bf16 v[88:91], v[178:181], v[218:221], v[88:91]
	v_mfma_f32_16x16x32_bf16 v[84:87], v[186:189], v[218:221], v[84:87]
	v_mfma_f32_16x16x32_bf16 v[72:75], v[178:181], v[230:233], v[72:75]
	v_mfma_f32_16x16x32_bf16 v[68:71], v[186:189], v[230:233], v[68:71]
	s_setprio 0
	s_barrier
	s_add_i32 s34, s68, s38
	v_lshl_add_u64 v[94:95], v[162:163], 0, s[24:25]
	s_mov_b32 m0, s34
	ds_read_b128 v[190:193], v153 offset:49152
	ds_read_b128 v[194:197], v153 offset:50176
	ds_read_b128 v[198:201], v153 offset:51200
	ds_read_b128 v[202:205], v153 offset:52224
	ds_read_b128 v[206:209], v153 offset:53248
	ds_read_b128 v[218:221], v153 offset:54272
	ds_read_b128 v[226:229], v153 offset:55296
	ds_read_b128 v[230:233], v153 offset:56320
	global_load_lds_dwordx4 v[94:95], off
	v_lshl_add_u64 v[94:95], v[210:211], 0, s[24:25]
	s_add_i32 m0, s34, 0x2000
	s_add_i32 s34, s69, s38
	global_load_lds_dwordx4 v[94:95], off
	v_lshl_add_u64 v[94:95], v[234:235], 0, s[24:25]
	s_mov_b32 m0, s34
	s_nop 0
	global_load_lds_dwordx4 v[94:95], off
	v_lshl_add_u64 v[94:95], v[236:237], 0, s[24:25]
	s_add_i32 m0, s34, 0x2000
	s_nop 0
	global_load_lds_dwordx4 v[94:95], off
	v_lshl_add_u64 v[94:95], v[238:239], 0, s[24:25]
	s_mov_b32 m0, s46
	s_nop 0
	global_load_lds_dwordx4 v[94:95], off
	v_lshl_add_u64 v[94:95], v[240:241], 0, s[24:25]
	s_mov_b32 m0, s47
	s_nop 0
	global_load_lds_dwordx4 v[94:95], off
	s_waitcnt vmcnt(8)
	s_waitcnt lgkmcnt(0)
	v_mfma_f32_16x16x32_bf16 v[64:67], v[154:157], v[190:193], v[64:67]
	v_mfma_f32_16x16x32_bf16 v[60:63], v[166:169], v[190:193], v[60:63]
	v_mfma_f32_16x16x32_bf16 v[48:51], v[154:157], v[198:201], v[48:51]
	v_mfma_f32_16x16x32_bf16 v[44:47], v[166:169], v[198:201], v[44:47]
	s_barrier
	s_setprio 1
	s_waitcnt lgkmcnt(0)
	v_mfma_f32_16x16x32_bf16 v[32:35], v[154:157], v[206:209], v[32:35]
	v_mfma_f32_16x16x32_bf16 v[28:31], v[166:169], v[206:209], v[28:31]
	v_mfma_f32_16x16x32_bf16 v[16:19], v[154:157], v[226:229], v[16:19]
	v_mfma_f32_16x16x32_bf16 v[12:15], v[166:169], v[226:229], v[12:15]
	v_mfma_f32_16x16x32_bf16 v[64:67], v[158:161], v[194:197], v[64:67]
	v_mfma_f32_16x16x32_bf16 v[60:63], v[170:173], v[194:197], v[60:63]
	v_mfma_f32_16x16x32_bf16 v[48:51], v[158:161], v[202:205], v[48:51]
	v_mfma_f32_16x16x32_bf16 v[44:47], v[170:173], v[202:205], v[44:47]
	v_mfma_f32_16x16x32_bf16 v[32:35], v[158:161], v[218:221], v[32:35]
	v_mfma_f32_16x16x32_bf16 v[28:31], v[170:173], v[218:221], v[28:31]
	v_mfma_f32_16x16x32_bf16 v[16:19], v[158:161], v[230:233], v[16:19]
	v_mfma_f32_16x16x32_bf16 v[12:15], v[170:173], v[230:233], v[12:15]
	v_mfma_f32_16x16x32_bf16 v[56:59], v[174:177], v[190:193], v[56:59]
	v_mfma_f32_16x16x32_bf16 v[52:55], v[182:185], v[190:193], v[52:55]
	v_mfma_f32_16x16x32_bf16 v[40:43], v[174:177], v[198:201], v[40:43]
	v_mfma_f32_16x16x32_bf16 v[36:39], v[182:185], v[198:201], v[36:39]
	v_mfma_f32_16x16x32_bf16 v[24:27], v[174:177], v[206:209], v[24:27]
	v_mfma_f32_16x16x32_bf16 v[20:23], v[182:185], v[206:209], v[20:23]
	v_mfma_f32_16x16x32_bf16 v[8:11], v[174:177], v[226:229], v[8:11]
	v_mfma_f32_16x16x32_bf16 v[4:7], v[182:185], v[226:229], v[4:7]
	v_mfma_f32_16x16x32_bf16 v[56:59], v[178:181], v[194:197], v[56:59]
	v_mfma_f32_16x16x32_bf16 v[52:55], v[186:189], v[194:197], v[52:55]
	v_mfma_f32_16x16x32_bf16 v[40:43], v[178:181], v[202:205], v[40:43]
	v_mfma_f32_16x16x32_bf16 v[36:39], v[186:189], v[202:205], v[36:39]
	v_mfma_f32_16x16x32_bf16 v[24:27], v[178:181], v[218:221], v[24:27]
	v_mfma_f32_16x16x32_bf16 v[20:23], v[186:189], v[218:221], v[20:23]
	v_mfma_f32_16x16x32_bf16 v[8:11], v[178:181], v[230:233], v[8:11]
	v_mfma_f32_16x16x32_bf16 v[4:7], v[186:189], v[230:233], v[4:7]
	s_setprio 0
	s_barrier
	s_add_u32 s30, s30, 0x100
	s_addc_u32 s31, s31, 0
	s_add_u32 s65, s65, 0x100
	s_addc_u32 s66, s66, 0
	s_cmp_ge_i32 s67, s49
	s_mov_b32 s34, s67
	s_cbranch_scc0 .LBB0_936

.LBB0_1116:
	ds_read_b128 v[148:151], v160
	ds_read_b128 v[152:155], v160 offset:1024
	ds_read_b128 v[166:169], v160 offset:2048
	ds_read_b128 v[170:173], v160 offset:3072
	ds_read_b128 v[174:177], v161
	ds_read_b128 v[178:181], v161 offset:1024
	ds_read_b128 v[182:185], v161 offset:2048
	ds_read_b128 v[186:189], v161 offset:3072
	s_add_u32 s48, s4, 0xfffc0080
	s_addc_u32 s49, s5, -1
	s_cmp_eq_u32 s71, 12
	s_cselect_b32 s59, s39, s49
	s_cselect_b32 s58, s45, s48
	s_cselect_b32 s49, s37, s70
	s_cselect_b32 s48, s60, s61
	v_lshl_add_u64 v[210:211], s[4:5], 0, v[140:141]
	s_add_i32 m0, s47, 0xc000
	ds_read_b128 v[190:193], v162
	ds_read_b128 v[194:197], v162 offset:1024
	ds_read_b128 v[198:201], v162 offset:2048
	ds_read_b128 v[202:205], v162 offset:3072
	ds_read_b128 v[206:209], v162 offset:4096
	ds_read_b128 v[226:229], v162 offset:5120
	ds_read_b128 v[230:233], v162 offset:6144
	ds_read_b128 v[234:237], v162 offset:7168
	global_load_lds_dwordx4 v[210:211], off
	v_lshl_add_u64 v[210:211], s[4:5], 0, v[142:143]
	s_add_i32 m0, s47, 0xe000
	s_nop 0
	global_load_lds_dwordx4 v[210:211], off
	s_waitcnt vmcnt(8)
	s_waitcnt lgkmcnt(0)
	v_mfma_f32_16x16x32_bf16 v[128:131], v[148:151], v[190:193], v[128:131]
	v_mfma_f32_16x16x32_bf16 v[124:127], v[166:169], v[190:193], v[124:127]
	v_mfma_f32_16x16x32_bf16 v[112:115], v[148:151], v[198:201], v[112:115]
	v_mfma_f32_16x16x32_bf16 v[108:111], v[166:169], v[198:201], v[108:111]
	s_barrier
	s_setprio 1
	s_waitcnt lgkmcnt(0)
	v_mfma_f32_16x16x32_bf16 v[96:99], v[148:151], v[206:209], v[96:99]
	v_mfma_f32_16x16x32_bf16 v[92:95], v[166:169], v[206:209], v[92:95]
	v_mfma_f32_16x16x32_bf16 v[80:83], v[148:151], v[230:233], v[80:83]
	v_mfma_f32_16x16x32_bf16 v[76:79], v[166:169], v[230:233], v[76:79]
	v_mfma_f32_16x16x32_bf16 v[128:131], v[152:155], v[194:197], v[128:131]
	v_mfma_f32_16x16x32_bf16 v[124:127], v[170:173], v[194:197], v[124:127]
	v_mfma_f32_16x16x32_bf16 v[112:115], v[152:155], v[202:205], v[112:115]
	v_mfma_f32_16x16x32_bf16 v[108:111], v[170:173], v[202:205], v[108:111]
	v_mfma_f32_16x16x32_bf16 v[96:99], v[152:155], v[226:229], v[96:99]
	v_mfma_f32_16x16x32_bf16 v[92:95], v[170:173], v[226:229], v[92:95]
	v_mfma_f32_16x16x32_bf16 v[80:83], v[152:155], v[234:237], v[80:83]
	v_mfma_f32_16x16x32_bf16 v[76:79], v[170:173], v[234:237], v[76:79]
	v_mfma_f32_16x16x32_bf16 v[120:123], v[174:177], v[190:193], v[120:123]
	v_mfma_f32_16x16x32_bf16 v[116:119], v[182:185], v[190:193], v[116:119]
	v_mfma_f32_16x16x32_bf16 v[104:107], v[174:177], v[198:201], v[104:107]
	v_mfma_f32_16x16x32_bf16 v[100:103], v[182:185], v[198:201], v[100:103]
	v_mfma_f32_16x16x32_bf16 v[88:91], v[174:177], v[206:209], v[88:91]
	v_mfma_f32_16x16x32_bf16 v[84:87], v[182:185], v[206:209], v[84:87]
	v_mfma_f32_16x16x32_bf16 v[72:75], v[174:177], v[230:233], v[72:75]
	v_mfma_f32_16x16x32_bf16 v[68:71], v[182:185], v[230:233], v[68:71]
	v_mfma_f32_16x16x32_bf16 v[120:123], v[178:181], v[194:197], v[120:123]
	v_mfma_f32_16x16x32_bf16 v[116:119], v[186:189], v[194:197], v[116:119]
	v_mfma_f32_16x16x32_bf16 v[104:107], v[178:181], v[202:205], v[104:107]
	v_mfma_f32_16x16x32_bf16 v[100:103], v[186:189], v[202:205], v[100:103]
	v_mfma_f32_16x16x32_bf16 v[88:91], v[178:181], v[226:229], v[88:91]
	v_mfma_f32_16x16x32_bf16 v[84:87], v[186:189], v[226:229], v[84:87]
	v_mfma_f32_16x16x32_bf16 v[72:75], v[178:181], v[234:237], v[72:75]
	v_mfma_f32_16x16x32_bf16 v[68:71], v[186:189], v[234:237], v[68:71]
	s_setprio 0
	s_barrier
	s_add_i32 s72, s78, s3
	v_lshl_add_u64 v[210:211], s[48:49], 0, v[134:135]
	s_mov_b32 m0, s72
	ds_read_b128 v[190:193], v162 offset:16384
	ds_read_b128 v[194:197], v162 offset:17408
	ds_read_b128 v[198:201], v162 offset:18432
	ds_read_b128 v[202:205], v162 offset:19456
	ds_read_b128 v[206:209], v162 offset:20480
	ds_read_b128 v[226:229], v162 offset:21504
	ds_read_b128 v[230:233], v162 offset:22528
	ds_read_b128 v[234:237], v162 offset:23552
	global_load_lds_dwordx4 v[210:211], off
	s_add_i32 m0, s72, 0x2000
	s_add_u32 s72, s48, 0x40000
	v_lshl_add_u64 v[220:221], s[48:49], 0, v[138:139]
	s_addc_u32 s73, s49, 0
	s_add_i32 s74, s79, s3
	global_load_lds_dwordx4 v[220:221], off
	v_lshl_add_u64 v[238:239], s[72:73], 0, v[134:135]
	s_mov_b32 m0, s74
	v_lshl_add_u64 v[240:241], s[58:59], 0, v[136:137]
	global_load_lds_dwordx4 v[238:239], off
	v_lshl_add_u64 v[238:239], s[72:73], 0, v[138:139]
	s_add_i32 m0, s74, 0x2000
	s_nop 0
	global_load_lds_dwordx4 v[238:239], off
	v_lshl_add_u64 v[238:239], s[58:59], 0, v[132:133]
	s_mov_b32 m0, s47
	s_nop 0
	global_load_lds_dwordx4 v[238:239], off
	s_mov_b32 m0, s51
	s_nop 0
	global_load_lds_dwordx4 v[240:241], off
	s_waitcnt vmcnt(8)
	s_waitcnt lgkmcnt(0)
	v_mfma_f32_16x16x32_bf16 v[64:67], v[148:151], v[190:193], v[64:67]
	v_mfma_f32_16x16x32_bf16 v[60:63], v[166:169], v[190:193], v[60:63]
	v_mfma_f32_16x16x32_bf16 v[48:51], v[148:151], v[198:201], v[48:51]
	v_mfma_f32_16x16x32_bf16 v[44:47], v[166:169], v[198:201], v[44:47]
	s_barrier
	s_setprio 1
	s_waitcnt lgkmcnt(0)
	v_mfma_f32_16x16x32_bf16 v[32:35], v[148:151], v[206:209], v[32:35]
	v_mfma_f32_16x16x32_bf16 v[28:31], v[166:169], v[206:209], v[28:31]
	v_mfma_f32_16x16x32_bf16 v[16:19], v[148:151], v[230:233], v[16:19]
	v_mfma_f32_16x16x32_bf16 v[12:15], v[166:169], v[230:233], v[12:15]
	v_mfma_f32_16x16x32_bf16 v[64:67], v[152:155], v[194:197], v[64:67]
	v_mfma_f32_16x16x32_bf16 v[60:63], v[170:173], v[194:197], v[60:63]
	v_mfma_f32_16x16x32_bf16 v[48:51], v[152:155], v[202:205], v[48:51]
	v_mfma_f32_16x16x32_bf16 v[44:47], v[170:173], v[202:205], v[44:47]
	v_mfma_f32_16x16x32_bf16 v[32:35], v[152:155], v[226:229], v[32:35]
	v_mfma_f32_16x16x32_bf16 v[28:31], v[170:173], v[226:229], v[28:31]
	v_mfma_f32_16x16x32_bf16 v[16:19], v[152:155], v[234:237], v[16:19]
	v_mfma_f32_16x16x32_bf16 v[12:15], v[170:173], v[234:237], v[12:15]
	v_mfma_f32_16x16x32_bf16 v[56:59], v[174:177], v[190:193], v[56:59]
	v_mfma_f32_16x16x32_bf16 v[52:55], v[182:185], v[190:193], v[52:55]
	v_mfma_f32_16x16x32_bf16 v[40:43], v[174:177], v[198:201], v[40:43]
	v_mfma_f32_16x16x32_bf16 v[36:39], v[182:185], v[198:201], v[36:39]
	v_mfma_f32_16x16x32_bf16 v[24:27], v[174:177], v[206:209], v[24:27]
	v_mfma_f32_16x16x32_bf16 v[20:23], v[182:185], v[206:209], v[20:23]
	v_mfma_f32_16x16x32_bf16 v[8:11], v[174:177], v[230:233], v[8:11]
	v_mfma_f32_16x16x32_bf16 v[4:7], v[182:185], v[230:233], v[4:7]
	v_mfma_f32_16x16x32_bf16 v[56:59], v[178:181], v[194:197], v[56:59]
	v_mfma_f32_16x16x32_bf16 v[52:55], v[186:189], v[194:197], v[52:55]
	v_mfma_f32_16x16x32_bf16 v[40:43], v[178:181], v[202:205], v[40:43]
	v_mfma_f32_16x16x32_bf16 v[36:39], v[186:189], v[202:205], v[36:39]
	v_mfma_f32_16x16x32_bf16 v[24:27], v[178:181], v[226:229], v[24:27]
	v_mfma_f32_16x16x32_bf16 v[20:23], v[186:189], v[226:229], v[20:23]
	v_mfma_f32_16x16x32_bf16 v[8:11], v[178:181], v[234:237], v[8:11]
	v_mfma_f32_16x16x32_bf16 v[4:7], v[186:189], v[234:237], v[4:7]
	s_setprio 0
	s_barrier
	s_add_i32 s72, 0, 0x18000
	v_add_u32_e32 v165, s72, v3
	s_add_i32 s73, 0, 0x1c000
	ds_read_b128 v[148:151], v165
	ds_read_b128 v[152:155], v165 offset:1024
	ds_read_b128 v[166:169], v165 offset:2048
	ds_read_b128 v[170:173], v165 offset:3072
	v_add_u32_e32 v165, s73, v3
	ds_read_b128 v[174:177], v165
	ds_read_b128 v[178:181], v165 offset:1024
	ds_read_b128 v[182:185], v165 offset:2048
	ds_read_b128 v[186:189], v165 offset:3072
	s_add_u32 s58, s58, 0x40000
	s_addc_u32 s59, s59, 0
	s_mov_b32 m0, s64
	v_lshl_add_u64 v[242:243], s[58:59], 0, v[132:133]
	ds_read_b128 v[190:193], v162 offset:32768
	ds_read_b128 v[194:197], v162 offset:33792
	ds_read_b128 v[198:201], v162 offset:34816
	ds_read_b128 v[202:205], v162 offset:35840
	ds_read_b128 v[206:209], v162 offset:36864
	ds_read_b128 v[226:229], v162 offset:37888
	ds_read_b128 v[230:233], v162 offset:38912
	ds_read_b128 v[234:237], v162 offset:39936
	global_load_lds_dwordx4 v[242:243], off
	v_lshl_add_u64 v[242:243], s[58:59], 0, v[136:137]
	s_mov_b32 m0, s65
	s_nop 0
	global_load_lds_dwordx4 v[242:243], off
	s_waitcnt vmcnt(8)
	s_waitcnt lgkmcnt(0)
	v_mfma_f32_16x16x32_bf16 v[128:131], v[148:151], v[190:193], v[128:131]
	v_mfma_f32_16x16x32_bf16 v[124:127], v[166:169], v[190:193], v[124:127]
	v_mfma_f32_16x16x32_bf16 v[112:115], v[148:151], v[198:201], v[112:115]
	v_mfma_f32_16x16x32_bf16 v[108:111], v[166:169], v[198:201], v[108:111]
	s_barrier
	s_setprio 1
	s_waitcnt lgkmcnt(0)
	v_mfma_f32_16x16x32_bf16 v[96:99], v[148:151], v[206:209], v[96:99]
	v_mfma_f32_16x16x32_bf16 v[92:95], v[166:169], v[206:209], v[92:95]
	v_mfma_f32_16x16x32_bf16 v[80:83], v[148:151], v[230:233], v[80:83]
	v_mfma_f32_16x16x32_bf16 v[76:79], v[166:169], v[230:233], v[76:79]
	v_mfma_f32_16x16x32_bf16 v[128:131], v[152:155], v[194:197], v[128:131]
	v_mfma_f32_16x16x32_bf16 v[124:127], v[170:173], v[194:197], v[124:127]
	v_mfma_f32_16x16x32_bf16 v[112:115], v[152:155], v[202:205], v[112:115]
	v_mfma_f32_16x16x32_bf16 v[108:111], v[170:173], v[202:205], v[108:111]
	v_mfma_f32_16x16x32_bf16 v[96:99], v[152:155], v[226:229], v[96:99]
	v_mfma_f32_16x16x32_bf16 v[92:95], v[170:173], v[226:229], v[92:95]
	v_mfma_f32_16x16x32_bf16 v[80:83], v[152:155], v[234:237], v[80:83]
	v_mfma_f32_16x16x32_bf16 v[76:79], v[170:173], v[234:237], v[76:79]
	v_mfma_f32_16x16x32_bf16 v[120:123], v[174:177], v[190:193], v[120:123]
	v_mfma_f32_16x16x32_bf16 v[116:119], v[182:185], v[190:193], v[116:119]
	v_mfma_f32_16x16x32_bf16 v[104:107], v[174:177], v[198:201], v[104:107]
	v_mfma_f32_16x16x32_bf16 v[100:103], v[182:185], v[198:201], v[100:103]
	v_mfma_f32_16x16x32_bf16 v[88:91], v[174:177], v[206:209], v[88:91]
	v_mfma_f32_16x16x32_bf16 v[84:87], v[182:185], v[206:209], v[84:87]
	v_mfma_f32_16x16x32_bf16 v[72:75], v[174:177], v[230:233], v[72:75]
	v_mfma_f32_16x16x32_bf16 v[68:71], v[182:185], v[230:233], v[68:71]
	v_mfma_f32_16x16x32_bf16 v[120:123], v[178:181], v[194:197], v[120:123]
	v_mfma_f32_16x16x32_bf16 v[116:119], v[186:189], v[194:197], v[116:119]
	v_mfma_f32_16x16x32_bf16 v[104:107], v[178:181], v[202:205], v[104:107]
	v_mfma_f32_16x16x32_bf16 v[100:103], v[186:189], v[202:205], v[100:103]
	v_mfma_f32_16x16x32_bf16 v[88:91], v[178:181], v[226:229], v[88:91]
	v_mfma_f32_16x16x32_bf16 v[84:87], v[186:189], v[226:229], v[84:87]
	v_mfma_f32_16x16x32_bf16 v[72:75], v[178:181], v[234:237], v[72:75]
	v_mfma_f32_16x16x32_bf16 v[68:71], v[186:189], v[234:237], v[68:71]
	s_setprio 0
	s_barrier
	s_add_i32 s58, s72, s3
	v_lshl_add_u64 v[210:211], v[210:211], 0, s[22:23]
	s_mov_b32 m0, s58
	ds_read_b128 v[190:193], v162 offset:49152
	ds_read_b128 v[194:197], v162 offset:50176
	ds_read_b128 v[198:201], v162 offset:51200
	ds_read_b128 v[202:205], v162 offset:52224
	ds_read_b128 v[206:209], v162 offset:53248
	ds_read_b128 v[226:229], v162 offset:54272
	ds_read_b128 v[230:233], v162 offset:55296
	ds_read_b128 v[234:237], v162 offset:56320
	global_load_lds_dwordx4 v[210:211], off
	s_add_i32 m0, s58, 0x2000
	s_add_u32 s48, s48, 0x40080
	v_lshl_add_u64 v[210:211], v[220:221], 0, s[22:23]
	s_addc_u32 s49, s49, 0
	s_add_i32 s58, s73, s3
	global_load_lds_dwordx4 v[210:211], off
	v_lshl_add_u64 v[210:211], s[48:49], 0, v[134:135]
	s_mov_b32 m0, s58
	s_nop 0
	global_load_lds_dwordx4 v[210:211], off
	v_lshl_add_u64 v[210:211], s[48:49], 0, v[138:139]
	s_add_i32 m0, s58, 0x2000
	s_nop 0
	global_load_lds_dwordx4 v[210:211], off
	v_lshl_add_u64 v[210:211], v[238:239], 0, s[22:23]
	s_mov_b32 m0, s68
	s_nop 0
	global_load_lds_dwordx4 v[210:211], off
	v_lshl_add_u64 v[210:211], v[240:241], 0, s[22:23]
	s_mov_b32 m0, s69
	s_nop 0
	global_load_lds_dwordx4 v[210:211], off
	s_waitcnt vmcnt(8)
	s_waitcnt lgkmcnt(0)
	v_mfma_f32_16x16x32_bf16 v[64:67], v[148:151], v[190:193], v[64:67]
	v_mfma_f32_16x16x32_bf16 v[60:63], v[166:169], v[190:193], v[60:63]
	v_mfma_f32_16x16x32_bf16 v[48:51], v[148:151], v[198:201], v[48:51]
	v_mfma_f32_16x16x32_bf16 v[44:47], v[166:169], v[198:201], v[44:47]
	s_barrier
	s_setprio 1
	s_waitcnt lgkmcnt(0)
	v_mfma_f32_16x16x32_bf16 v[32:35], v[148:151], v[206:209], v[32:35]
	v_mfma_f32_16x16x32_bf16 v[28:31], v[166:169], v[206:209], v[28:31]
	v_mfma_f32_16x16x32_bf16 v[16:19], v[148:151], v[230:233], v[16:19]
	v_mfma_f32_16x16x32_bf16 v[12:15], v[166:169], v[230:233], v[12:15]
	v_mfma_f32_16x16x32_bf16 v[64:67], v[152:155], v[194:197], v[64:67]
	v_mfma_f32_16x16x32_bf16 v[60:63], v[170:173], v[194:197], v[60:63]
	v_mfma_f32_16x16x32_bf16 v[48:51], v[152:155], v[202:205], v[48:51]
	v_mfma_f32_16x16x32_bf16 v[44:47], v[170:173], v[202:205], v[44:47]
	v_mfma_f32_16x16x32_bf16 v[32:35], v[152:155], v[226:229], v[32:35]
	v_mfma_f32_16x16x32_bf16 v[28:31], v[170:173], v[226:229], v[28:31]
	v_mfma_f32_16x16x32_bf16 v[16:19], v[152:155], v[234:237], v[16:19]
	v_mfma_f32_16x16x32_bf16 v[12:15], v[170:173], v[234:237], v[12:15]
	v_mfma_f32_16x16x32_bf16 v[56:59], v[174:177], v[190:193], v[56:59]
	v_mfma_f32_16x16x32_bf16 v[52:55], v[182:185], v[190:193], v[52:55]
	v_mfma_f32_16x16x32_bf16 v[40:43], v[174:177], v[198:201], v[40:43]
	v_mfma_f32_16x16x32_bf16 v[36:39], v[182:185], v[198:201], v[36:39]
	v_mfma_f32_16x16x32_bf16 v[24:27], v[174:177], v[206:209], v[24:27]
	v_mfma_f32_16x16x32_bf16 v[20:23], v[182:185], v[206:209], v[20:23]
	v_mfma_f32_16x16x32_bf16 v[8:11], v[174:177], v[230:233], v[8:11]
	v_mfma_f32_16x16x32_bf16 v[4:7], v[182:185], v[230:233], v[4:7]
	v_mfma_f32_16x16x32_bf16 v[56:59], v[178:181], v[194:197], v[56:59]
	v_mfma_f32_16x16x32_bf16 v[52:55], v[186:189], v[194:197], v[52:55]
	v_mfma_f32_16x16x32_bf16 v[40:43], v[178:181], v[202:205], v[40:43]
	v_mfma_f32_16x16x32_bf16 v[36:39], v[186:189], v[202:205], v[36:39]
	v_mfma_f32_16x16x32_bf16 v[24:27], v[178:181], v[226:229], v[24:27]
	v_mfma_f32_16x16x32_bf16 v[20:23], v[186:189], v[226:229], v[20:23]
	v_mfma_f32_16x16x32_bf16 v[8:11], v[178:181], v[234:237], v[8:11]
	v_mfma_f32_16x16x32_bf16 v[4:7], v[186:189], v[234:237], v[4:7]
	s_setprio 0
	s_barrier
	s_add_i32 s71, s71, 2
	s_add_u32 s4, s4, 0x100
	s_addc_u32 s5, s5, 0
	s_add_u32 s61, s61, 0x100
	s_addc_u32 s70, s70, 0
	s_cmp_gt_u32 s71, 13
	s_cbranch_scc0 .LBB0_1116
	s_and_b64 vcc, exec, s[24:25]
	s_cbranch_vccz .LBB0_1119
	s_barrier

.LBB0_1612:
	v_add_u32_e32 v160, s46, v150
	ds_read_b128 v[152:155], v160
	ds_read_b128 v[156:159], v160 offset:1024
	ds_read_b128 v[166:169], v160 offset:2048
	ds_read_b128 v[170:173], v160 offset:3072
	v_add_u32_e32 v160, s47, v150
	s_add_u32 s28, s14, s26
	ds_read_b128 v[174:177], v160
	ds_read_b128 v[178:181], v160 offset:1024
	ds_read_b128 v[182:185], v160 offset:2048
	ds_read_b128 v[186:189], v160 offset:3072
	s_addc_u32 s29, s15, s27
	s_add_u32 s28, s28, 0x100
	s_addc_u32 s29, s29, 0
	s_add_u32 s60, s49, s26
	s_addc_u32 s61, s50, s27
	s_cmpk_eq_i32 s26, 0x700
	s_cselect_b32 s31, s21, s29
	s_cselect_b32 s30, s51, s28
	s_cselect_b32 s29, s19, s61
	s_cselect_b32 s28, s58, s60
	v_lshl_add_u64 v[160:161], v[146:147], 0, s[26:27]
	s_add_i32 m0, s38, 0xc000
	ds_read_b128 v[190:193], v151
	ds_read_b128 v[194:197], v151 offset:1024
	ds_read_b128 v[198:201], v151 offset:2048
	ds_read_b128 v[202:205], v151 offset:3072
	ds_read_b128 v[206:209], v151 offset:4096
	ds_read_b128 v[226:229], v151 offset:5120
	ds_read_b128 v[230:233], v151 offset:6144
	ds_read_b128 v[234:237], v151 offset:7168
	global_load_lds_dwordx4 v[160:161], off
	v_lshl_add_u64 v[160:161], v[148:149], 0, s[26:27]
	s_add_i32 m0, s38, 0xe000
	s_nop 0
	global_load_lds_dwordx4 v[160:161], off
	s_waitcnt vmcnt(8)
	s_waitcnt lgkmcnt(0)
	v_mfma_f32_16x16x32_bf16 v[122:125], v[152:155], v[190:193], v[122:125]
	v_mfma_f32_16x16x32_bf16 v[126:129], v[166:169], v[190:193], v[126:129]
	v_mfma_f32_16x16x32_bf16 v[110:113], v[152:155], v[198:201], v[110:113]
	v_mfma_f32_16x16x32_bf16 v[106:109], v[166:169], v[198:201], v[106:109]
	s_barrier
	s_setprio 1
	s_waitcnt lgkmcnt(0)
	v_mfma_f32_16x16x32_bf16 v[94:97], v[152:155], v[206:209], v[94:97]
	v_mfma_f32_16x16x32_bf16 v[90:93], v[166:169], v[206:209], v[90:93]
	v_mfma_f32_16x16x32_bf16 v[78:81], v[152:155], v[230:233], v[78:81]
	v_mfma_f32_16x16x32_bf16 v[74:77], v[166:169], v[230:233], v[74:77]
	v_mfma_f32_16x16x32_bf16 v[122:125], v[156:159], v[194:197], v[122:125]
	v_mfma_f32_16x16x32_bf16 v[126:129], v[170:173], v[194:197], v[126:129]
	v_mfma_f32_16x16x32_bf16 v[110:113], v[156:159], v[202:205], v[110:113]
	v_mfma_f32_16x16x32_bf16 v[106:109], v[170:173], v[202:205], v[106:109]
	v_mfma_f32_16x16x32_bf16 v[94:97], v[156:159], v[226:229], v[94:97]
	v_mfma_f32_16x16x32_bf16 v[90:93], v[170:173], v[226:229], v[90:93]
	v_mfma_f32_16x16x32_bf16 v[78:81], v[156:159], v[234:237], v[78:81]
	v_mfma_f32_16x16x32_bf16 v[74:77], v[170:173], v[234:237], v[74:77]
	v_mfma_f32_16x16x32_bf16 v[118:121], v[174:177], v[190:193], v[118:121]
	v_mfma_f32_16x16x32_bf16 v[114:117], v[182:185], v[190:193], v[114:117]
	v_mfma_f32_16x16x32_bf16 v[102:105], v[174:177], v[198:201], v[102:105]
	v_mfma_f32_16x16x32_bf16 v[98:101], v[182:185], v[198:201], v[98:101]
	v_mfma_f32_16x16x32_bf16 v[86:89], v[174:177], v[206:209], v[86:89]
	v_mfma_f32_16x16x32_bf16 v[82:85], v[182:185], v[206:209], v[82:85]
	v_mfma_f32_16x16x32_bf16 v[70:73], v[174:177], v[230:233], v[70:73]
	v_mfma_f32_16x16x32_bf16 v[66:69], v[182:185], v[230:233], v[66:69]
	v_mfma_f32_16x16x32_bf16 v[118:121], v[178:181], v[194:197], v[118:121]
	v_mfma_f32_16x16x32_bf16 v[114:117], v[186:189], v[194:197], v[114:117]
	v_mfma_f32_16x16x32_bf16 v[102:105], v[178:181], v[202:205], v[102:105]
	v_mfma_f32_16x16x32_bf16 v[98:101], v[186:189], v[202:205], v[98:101]
	v_mfma_f32_16x16x32_bf16 v[86:89], v[178:181], v[226:229], v[86:89]
	v_mfma_f32_16x16x32_bf16 v[82:85], v[186:189], v[226:229], v[82:85]
	v_mfma_f32_16x16x32_bf16 v[70:73], v[178:181], v[234:237], v[70:73]
	v_mfma_f32_16x16x32_bf16 v[66:69], v[186:189], v[234:237], v[66:69]
	s_setprio 0
	s_barrier
	s_add_i32 s60, s46, s37
	v_lshl_add_u64 v[160:161], s[28:29], 0, v[132:133]
	s_mov_b32 m0, s60
	ds_read_b128 v[190:193], v151 offset:16384
	ds_read_b128 v[194:197], v151 offset:17408
	ds_read_b128 v[198:201], v151 offset:18432
	ds_read_b128 v[202:205], v151 offset:19456
	ds_read_b128 v[206:209], v151 offset:20480
	ds_read_b128 v[226:229], v151 offset:21504
	ds_read_b128 v[230:233], v151 offset:22528
	ds_read_b128 v[234:237], v151 offset:23552
	global_load_lds_dwordx4 v[160:161], off
	s_add_i32 m0, s60, 0x2000
	s_add_u32 s60, s28, 0x40000
	v_lshl_add_u64 v[210:211], s[28:29], 0, v[136:137]
	s_addc_u32 s61, s29, 0
	s_add_i32 s64, s47, s37
	global_load_lds_dwordx4 v[210:211], off
	v_lshl_add_u64 v[214:215], s[60:61], 0, v[132:133]
	s_mov_b32 m0, s64
	v_lshl_add_u64 v[220:221], s[30:31], 0, v[134:135]
	global_load_lds_dwordx4 v[214:215], off
	v_lshl_add_u64 v[214:215], s[60:61], 0, v[136:137]
	s_add_i32 m0, s64, 0x2000
	s_nop 0
	global_load_lds_dwordx4 v[214:215], off
	v_lshl_add_u64 v[214:215], s[30:31], 0, v[130:131]
	s_mov_b32 m0, s38
	s_nop 0
	global_load_lds_dwordx4 v[214:215], off
	s_mov_b32 m0, s39
	s_nop 0
	global_load_lds_dwordx4 v[220:221], off
	s_waitcnt vmcnt(8)
	s_waitcnt lgkmcnt(0)
	v_mfma_f32_16x16x32_bf16 v[62:65], v[152:155], v[190:193], v[62:65]
	v_mfma_f32_16x16x32_bf16 v[58:61], v[166:169], v[190:193], v[58:61]
	v_mfma_f32_16x16x32_bf16 v[46:49], v[152:155], v[198:201], v[46:49]
	v_mfma_f32_16x16x32_bf16 v[42:45], v[166:169], v[198:201], v[42:45]
	s_barrier
	s_setprio 1
	s_waitcnt lgkmcnt(0)
	v_mfma_f32_16x16x32_bf16 v[30:33], v[152:155], v[206:209], v[30:33]
	v_mfma_f32_16x16x32_bf16 v[26:29], v[166:169], v[206:209], v[26:29]
	v_mfma_f32_16x16x32_bf16 v[14:17], v[152:155], v[230:233], v[14:17]
	v_mfma_f32_16x16x32_bf16 v[10:13], v[166:169], v[230:233], v[10:13]
	v_mfma_f32_16x16x32_bf16 v[62:65], v[156:159], v[194:197], v[62:65]
	v_mfma_f32_16x16x32_bf16 v[58:61], v[170:173], v[194:197], v[58:61]
	v_mfma_f32_16x16x32_bf16 v[46:49], v[156:159], v[202:205], v[46:49]
	v_mfma_f32_16x16x32_bf16 v[42:45], v[170:173], v[202:205], v[42:45]
	v_mfma_f32_16x16x32_bf16 v[30:33], v[156:159], v[226:229], v[30:33]
	v_mfma_f32_16x16x32_bf16 v[26:29], v[170:173], v[226:229], v[26:29]
	v_mfma_f32_16x16x32_bf16 v[14:17], v[156:159], v[234:237], v[14:17]
	v_mfma_f32_16x16x32_bf16 v[10:13], v[170:173], v[234:237], v[10:13]
	v_mfma_f32_16x16x32_bf16 v[54:57], v[174:177], v[190:193], v[54:57]
	v_mfma_f32_16x16x32_bf16 v[50:53], v[182:185], v[190:193], v[50:53]
	v_mfma_f32_16x16x32_bf16 v[38:41], v[174:177], v[198:201], v[38:41]
	v_mfma_f32_16x16x32_bf16 v[34:37], v[182:185], v[198:201], v[34:37]
	v_mfma_f32_16x16x32_bf16 v[22:25], v[174:177], v[206:209], v[22:25]
	v_mfma_f32_16x16x32_bf16 v[18:21], v[182:185], v[206:209], v[18:21]
	v_mfma_f32_16x16x32_bf16 v[6:9], v[174:177], v[230:233], v[6:9]
	v_mfma_f32_16x16x32_bf16 v[2:5], v[182:185], v[230:233], v[2:5]
	v_mfma_f32_16x16x32_bf16 v[54:57], v[178:181], v[194:197], v[54:57]
	v_mfma_f32_16x16x32_bf16 v[50:53], v[186:189], v[194:197], v[50:53]
	v_mfma_f32_16x16x32_bf16 v[38:41], v[178:181], v[202:205], v[38:41]
	v_mfma_f32_16x16x32_bf16 v[34:37], v[186:189], v[202:205], v[34:37]
	v_mfma_f32_16x16x32_bf16 v[22:25], v[178:181], v[226:229], v[22:25]
	v_mfma_f32_16x16x32_bf16 v[18:21], v[186:189], v[226:229], v[18:21]
	v_mfma_f32_16x16x32_bf16 v[6:9], v[178:181], v[234:237], v[6:9]
	v_mfma_f32_16x16x32_bf16 v[2:5], v[186:189], v[234:237], v[2:5]
	s_setprio 0
	s_barrier
	s_add_i32 s60, 0, 0x18000
	v_add_u32_e32 v163, s60, v150
	s_add_i32 s61, 0, 0x1c000
	ds_read_b128 v[152:155], v163
	ds_read_b128 v[156:159], v163 offset:1024
	ds_read_b128 v[166:169], v163 offset:2048
	ds_read_b128 v[170:173], v163 offset:3072
	v_add_u32_e32 v163, s61, v150
	ds_read_b128 v[174:177], v163
	ds_read_b128 v[178:181], v163 offset:1024
	ds_read_b128 v[182:185], v163 offset:2048
	ds_read_b128 v[186:189], v163 offset:3072
	s_add_u32 s30, s30, 0x40000
	s_addc_u32 s31, s31, 0
	s_mov_b32 m0, s40
	v_lshl_add_u64 v[238:239], s[30:31], 0, v[130:131]
	ds_read_b128 v[190:193], v151 offset:32768
	ds_read_b128 v[194:197], v151 offset:33792
	ds_read_b128 v[198:201], v151 offset:34816
	ds_read_b128 v[202:205], v151 offset:35840
	ds_read_b128 v[206:209], v151 offset:36864
	ds_read_b128 v[226:229], v151 offset:37888
	ds_read_b128 v[230:233], v151 offset:38912
	ds_read_b128 v[234:237], v151 offset:39936
	global_load_lds_dwordx4 v[238:239], off
	v_lshl_add_u64 v[238:239], s[30:31], 0, v[134:135]
	s_mov_b32 m0, s41
	s_nop 0
	global_load_lds_dwordx4 v[238:239], off
	s_waitcnt vmcnt(8)
	s_waitcnt lgkmcnt(0)
	v_mfma_f32_16x16x32_bf16 v[122:125], v[152:155], v[190:193], v[122:125]
	v_mfma_f32_16x16x32_bf16 v[126:129], v[166:169], v[190:193], v[126:129]
	v_mfma_f32_16x16x32_bf16 v[110:113], v[152:155], v[198:201], v[110:113]
	v_mfma_f32_16x16x32_bf16 v[106:109], v[166:169], v[198:201], v[106:109]
	s_barrier
	s_setprio 1
	s_waitcnt lgkmcnt(0)
	v_mfma_f32_16x16x32_bf16 v[94:97], v[152:155], v[206:209], v[94:97]
	v_mfma_f32_16x16x32_bf16 v[90:93], v[166:169], v[206:209], v[90:93]
	v_mfma_f32_16x16x32_bf16 v[78:81], v[152:155], v[230:233], v[78:81]
	v_mfma_f32_16x16x32_bf16 v[74:77], v[166:169], v[230:233], v[74:77]
	v_mfma_f32_16x16x32_bf16 v[122:125], v[156:159], v[194:197], v[122:125]
	v_mfma_f32_16x16x32_bf16 v[126:129], v[170:173], v[194:197], v[126:129]
	v_mfma_f32_16x16x32_bf16 v[110:113], v[156:159], v[202:205], v[110:113]
	v_mfma_f32_16x16x32_bf16 v[106:109], v[170:173], v[202:205], v[106:109]
	v_mfma_f32_16x16x32_bf16 v[94:97], v[156:159], v[226:229], v[94:97]
	v_mfma_f32_16x16x32_bf16 v[90:93], v[170:173], v[226:229], v[90:93]
	v_mfma_f32_16x16x32_bf16 v[78:81], v[156:159], v[234:237], v[78:81]
	v_mfma_f32_16x16x32_bf16 v[74:77], v[170:173], v[234:237], v[74:77]
	v_mfma_f32_16x16x32_bf16 v[118:121], v[174:177], v[190:193], v[118:121]
	v_mfma_f32_16x16x32_bf16 v[114:117], v[182:185], v[190:193], v[114:117]
	v_mfma_f32_16x16x32_bf16 v[102:105], v[174:177], v[198:201], v[102:105]
	v_mfma_f32_16x16x32_bf16 v[98:101], v[182:185], v[198:201], v[98:101]
	v_mfma_f32_16x16x32_bf16 v[86:89], v[174:177], v[206:209], v[86:89]
	v_mfma_f32_16x16x32_bf16 v[82:85], v[182:185], v[206:209], v[82:85]
	v_mfma_f32_16x16x32_bf16 v[70:73], v[174:177], v[230:233], v[70:73]
	v_mfma_f32_16x16x32_bf16 v[66:69], v[182:185], v[230:233], v[66:69]
	v_mfma_f32_16x16x32_bf16 v[118:121], v[178:181], v[194:197], v[118:121]
	v_mfma_f32_16x16x32_bf16 v[114:117], v[186:189], v[194:197], v[114:117]
	v_mfma_f32_16x16x32_bf16 v[102:105], v[178:181], v[202:205], v[102:105]
	v_mfma_f32_16x16x32_bf16 v[98:101], v[186:189], v[202:205], v[98:101]
	v_mfma_f32_16x16x32_bf16 v[86:89], v[178:181], v[226:229], v[86:89]
	v_mfma_f32_16x16x32_bf16 v[82:85], v[186:189], v[226:229], v[82:85]
	v_mfma_f32_16x16x32_bf16 v[70:73], v[178:181], v[234:237], v[70:73]
	v_mfma_f32_16x16x32_bf16 v[66:69], v[186:189], v[234:237], v[66:69]
	s_setprio 0
	s_barrier
	s_add_i32 s30, s60, s37
	v_lshl_add_u64 v[160:161], v[160:161], 0, s[16:17]
	s_mov_b32 m0, s30
	ds_read_b128 v[190:193], v151 offset:49152
	ds_read_b128 v[194:197], v151 offset:50176
	ds_read_b128 v[198:201], v151 offset:51200
	ds_read_b128 v[202:205], v151 offset:52224
	ds_read_b128 v[206:209], v151 offset:53248
	ds_read_b128 v[226:229], v151 offset:54272
	ds_read_b128 v[230:233], v151 offset:55296
	ds_read_b128 v[234:237], v151 offset:56320
	global_load_lds_dwordx4 v[160:161], off
	s_add_i32 m0, s30, 0x2000
	s_add_u32 s28, s28, 0x40080
	v_lshl_add_u64 v[160:161], v[210:211], 0, s[16:17]
	s_addc_u32 s29, s29, 0
	s_add_i32 s30, s61, s37
	global_load_lds_dwordx4 v[160:161], off
	v_lshl_add_u64 v[160:161], s[28:29], 0, v[132:133]
	s_mov_b32 m0, s30
	s_nop 0
	global_load_lds_dwordx4 v[160:161], off
	v_lshl_add_u64 v[160:161], s[28:29], 0, v[136:137]
	s_add_i32 m0, s30, 0x2000
	s_nop 0
	global_load_lds_dwordx4 v[160:161], off
	v_lshl_add_u64 v[160:161], v[214:215], 0, s[16:17]
	s_mov_b32 m0, s43
	s_nop 0
	global_load_lds_dwordx4 v[160:161], off
	v_lshl_add_u64 v[160:161], v[220:221], 0, s[16:17]
	s_mov_b32 m0, s44
	s_nop 0
	global_load_lds_dwordx4 v[160:161], off
	s_waitcnt vmcnt(8)
	s_waitcnt lgkmcnt(0)
	v_mfma_f32_16x16x32_bf16 v[62:65], v[152:155], v[190:193], v[62:65]
	v_mfma_f32_16x16x32_bf16 v[58:61], v[166:169], v[190:193], v[58:61]
	v_mfma_f32_16x16x32_bf16 v[46:49], v[152:155], v[198:201], v[46:49]
	v_mfma_f32_16x16x32_bf16 v[42:45], v[166:169], v[198:201], v[42:45]
	s_barrier
	s_setprio 1
	s_waitcnt lgkmcnt(0)
	v_mfma_f32_16x16x32_bf16 v[30:33], v[152:155], v[206:209], v[30:33]
	v_mfma_f32_16x16x32_bf16 v[26:29], v[166:169], v[206:209], v[26:29]
	v_mfma_f32_16x16x32_bf16 v[14:17], v[152:155], v[230:233], v[14:17]
	v_mfma_f32_16x16x32_bf16 v[10:13], v[166:169], v[230:233], v[10:13]
	v_mfma_f32_16x16x32_bf16 v[62:65], v[156:159], v[194:197], v[62:65]
	v_mfma_f32_16x16x32_bf16 v[58:61], v[170:173], v[194:197], v[58:61]
	v_mfma_f32_16x16x32_bf16 v[46:49], v[156:159], v[202:205], v[46:49]
	v_mfma_f32_16x16x32_bf16 v[42:45], v[170:173], v[202:205], v[42:45]
	v_mfma_f32_16x16x32_bf16 v[30:33], v[156:159], v[226:229], v[30:33]
	v_mfma_f32_16x16x32_bf16 v[26:29], v[170:173], v[226:229], v[26:29]
	v_mfma_f32_16x16x32_bf16 v[14:17], v[156:159], v[234:237], v[14:17]
	v_mfma_f32_16x16x32_bf16 v[10:13], v[170:173], v[234:237], v[10:13]
	v_mfma_f32_16x16x32_bf16 v[54:57], v[174:177], v[190:193], v[54:57]
	v_mfma_f32_16x16x32_bf16 v[50:53], v[182:185], v[190:193], v[50:53]
	v_mfma_f32_16x16x32_bf16 v[38:41], v[174:177], v[198:201], v[38:41]
	v_mfma_f32_16x16x32_bf16 v[34:37], v[182:185], v[198:201], v[34:37]
	v_mfma_f32_16x16x32_bf16 v[22:25], v[174:177], v[206:209], v[22:25]
	v_mfma_f32_16x16x32_bf16 v[18:21], v[182:185], v[206:209], v[18:21]
	v_mfma_f32_16x16x32_bf16 v[6:9], v[174:177], v[230:233], v[6:9]
	v_mfma_f32_16x16x32_bf16 v[2:5], v[182:185], v[230:233], v[2:5]
	v_mfma_f32_16x16x32_bf16 v[54:57], v[178:181], v[194:197], v[54:57]
	v_mfma_f32_16x16x32_bf16 v[50:53], v[186:189], v[194:197], v[50:53]
	v_mfma_f32_16x16x32_bf16 v[38:41], v[178:181], v[202:205], v[38:41]
	v_mfma_f32_16x16x32_bf16 v[34:37], v[186:189], v[202:205], v[34:37]
	v_mfma_f32_16x16x32_bf16 v[22:25], v[178:181], v[226:229], v[22:25]
	v_mfma_f32_16x16x32_bf16 v[18:21], v[186:189], v[226:229], v[18:21]
	v_mfma_f32_16x16x32_bf16 v[6:9], v[178:181], v[234:237], v[6:9]
	v_mfma_f32_16x16x32_bf16 v[2:5], v[186:189], v[234:237], v[2:5]
	s_setprio 0
	s_barrier
	s_add_i32 s59, s59, 2
	s_add_u32 s26, s26, 0x100
	s_addc_u32 s27, s27, 0
	s_cmp_gt_u32 s59, 13
	s_cbranch_scc0 .LBB0_1612
	s_add_u32 s26, s49, 0xffffff00
	s_addc_u32 s27, s50, -1
	s_andn2_b64 vcc, exec, s[4:5]
	s_cbranch_vccnz .LBB0_1603
	v_mov_b32_e32 v2, 0
	s_mov_b32 s6, s18
	s_mov_b32 s12, s20
	s_mov_b64 s[14:15], s[24:25]
	s_mov_b32 s45, s48
	v_mov_b32_e32 v3, v2
	v_mov_b32_e32 v4, v2
	v_mov_b32_e32 v5, v2
	v_mov_b32_e32 v6, v2
	v_mov_b32_e32 v7, v2
	v_mov_b32_e32 v8, v2
	v_mov_b32_e32 v9, v2
	v_mov_b32_e32 v18, v2
	v_mov_b32_e32 v19, v2
	v_mov_b32_e32 v20, v2
	v_mov_b32_e32 v21, v2
	v_mov_b32_e32 v22, v2
	v_mov_b32_e32 v23, v2
	v_mov_b32_e32 v24, v2
	v_mov_b32_e32 v25, v2
	v_mov_b32_e32 v34, v2
	v_mov_b32_e32 v35, v2
	v_mov_b32_e32 v36, v2
	v_mov_b32_e32 v37, v2
	v_mov_b32_e32 v38, v2
	v_mov_b32_e32 v39, v2
	v_mov_b32_e32 v40, v2
	v_mov_b32_e32 v41, v2
	v_mov_b32_e32 v50, v2
	v_mov_b32_e32 v51, v2
	v_mov_b32_e32 v52, v2
	v_mov_b32_e32 v53, v2
	v_mov_b32_e32 v54, v2
	v_mov_b32_e32 v55, v2
	v_mov_b32_e32 v56, v2
	v_mov_b32_e32 v57, v2
	v_mov_b32_e32 v10, v2
	v_mov_b32_e32 v11, v2
	v_mov_b32_e32 v12, v2
	v_mov_b32_e32 v13, v2
	v_mov_b32_e32 v14, v2
	v_mov_b32_e32 v15, v2
	v_mov_b32_e32 v16, v2
	v_mov_b32_e32 v17, v2
	v_mov_b32_e32 v26, v2
	v_mov_b32_e32 v27, v2
	v_mov_b32_e32 v28, v2
	v_mov_b32_e32 v29, v2
	v_mov_b32_e32 v30, v2
	v_mov_b32_e32 v31, v2
	v_mov_b32_e32 v32, v2
	v_mov_b32_e32 v33, v2
	v_mov_b32_e32 v42, v2
	v_mov_b32_e32 v43, v2
	v_mov_b32_e32 v44, v2
	v_mov_b32_e32 v45, v2
	v_mov_b32_e32 v46, v2
	v_mov_b32_e32 v47, v2
	v_mov_b32_e32 v48, v2
	v_mov_b32_e32 v49, v2
	v_mov_b32_e32 v58, v2
	v_mov_b32_e32 v59, v2
	v_mov_b32_e32 v60, v2
	v_mov_b32_e32 v61, v2
	v_mov_b32_e32 v62, v2
	v_mov_b32_e32 v63, v2
	v_mov_b32_e32 v64, v2
	v_mov_b32_e32 v65, v2
	v_mov_b32_e32 v66, v2
	v_mov_b32_e32 v67, v2
	v_mov_b32_e32 v68, v2
	v_mov_b32_e32 v69, v2
	v_mov_b32_e32 v70, v2
	v_mov_b32_e32 v71, v2
	v_mov_b32_e32 v72, v2
	v_mov_b32_e32 v73, v2
	v_mov_b32_e32 v82, v2
	v_mov_b32_e32 v83, v2
	v_mov_b32_e32 v84, v2
	v_mov_b32_e32 v85, v2
	v_mov_b32_e32 v86, v2
	v_mov_b32_e32 v87, v2
	v_mov_b32_e32 v88, v2
	v_mov_b32_e32 v89, v2
	v_mov_b32_e32 v98, v2
	v_mov_b32_e32 v99, v2
	v_mov_b32_e32 v100, v2
	v_mov_b32_e32 v101, v2
	v_mov_b32_e32 v102, v2
	v_mov_b32_e32 v103, v2
	v_mov_b32_e32 v104, v2
	v_mov_b32_e32 v105, v2
	v_mov_b32_e32 v114, v2
	v_mov_b32_e32 v115, v2
	v_mov_b32_e32 v116, v2
	v_mov_b32_e32 v117, v2
	v_mov_b32_e32 v118, v2
	v_mov_b32_e32 v119, v2
	v_mov_b32_e32 v120, v2
	v_mov_b32_e32 v121, v2
	v_mov_b32_e32 v74, v2
	v_mov_b32_e32 v75, v2
	v_mov_b32_e32 v76, v2
	v_mov_b32_e32 v77, v2
	v_mov_b32_e32 v78, v2
	v_mov_b32_e32 v79, v2
	v_mov_b32_e32 v80, v2
	v_mov_b32_e32 v81, v2
	v_mov_b32_e32 v90, v2
	v_mov_b32_e32 v91, v2
	v_mov_b32_e32 v92, v2
	v_mov_b32_e32 v93, v2
	v_mov_b32_e32 v94, v2
	v_mov_b32_e32 v95, v2
	v_mov_b32_e32 v96, v2
	v_mov_b32_e32 v97, v2
	v_mov_b32_e32 v106, v2
	v_mov_b32_e32 v107, v2
	v_mov_b32_e32 v108, v2
	v_mov_b32_e32 v109, v2
	v_mov_b32_e32 v110, v2
	v_mov_b32_e32 v111, v2
	v_mov_b32_e32 v112, v2
	v_mov_b32_e32 v113, v2
	v_mov_b32_e32 v126, v2
	v_mov_b32_e32 v127, v2
	v_mov_b32_e32 v128, v2
	v_mov_b32_e32 v129, v2
	v_mov_b32_e32 v122, v2
	v_mov_b32_e32 v123, v2
	v_mov_b32_e32 v124, v2
	v_mov_b32_e32 v125, v2
	s_andn2_b64 vcc, exec, s[0:1]
	s_cbranch_vccnz .LBB0_1604

.LBB0_1753:
	ds_read_b128 v[146:149], v157
	ds_read_b128 v[160:163], v157 offset:1024
	ds_read_b128 v[164:167], v157 offset:2048
	ds_read_b128 v[168:171], v157 offset:3072
	ds_read_b128 v[172:175], v158
	ds_read_b128 v[176:179], v158 offset:1024
	ds_read_b128 v[180:183], v158 offset:2048
	ds_read_b128 v[184:187], v158 offset:3072
	s_add_u32 s38, s36, 0xfffc0080
	s_addc_u32 s39, s37, -1
	s_cmp_eq_u32 s65, 12
	s_cselect_b32 s41, s27, s39
	s_cselect_b32 s40, s59, s38
	s_cselect_b32 s39, s25, s64
	s_cselect_b32 s38, s60, s61
	v_lshl_add_u64 v[150:151], s[36:37], 0, v[138:139]
	s_add_i32 m0, s35, 0xc000
	ds_read_b128 v[188:191], v159
	ds_read_b128 v[192:195], v159 offset:1024
	ds_read_b128 v[196:199], v159 offset:2048
	ds_read_b128 v[200:203], v159 offset:3072
	ds_read_b128 v[204:207], v159 offset:4096
	ds_read_b128 v[208:211], v159 offset:5120
	ds_read_b128 v[218:221], v159 offset:6144
	ds_read_b128 v[226:229], v159 offset:7168
	global_load_lds_dwordx4 v[150:151], off
	v_lshl_add_u64 v[150:151], s[36:37], 0, v[140:141]
	s_add_i32 m0, s35, 0xe000
	s_nop 0
	global_load_lds_dwordx4 v[150:151], off
	s_waitcnt vmcnt(8)
	s_waitcnt lgkmcnt(0)
	v_mfma_f32_16x16x32_bf16 v[126:129], v[146:149], v[188:191], v[126:129]
	v_mfma_f32_16x16x32_bf16 v[122:125], v[164:167], v[188:191], v[122:125]
	v_mfma_f32_16x16x32_bf16 v[110:113], v[146:149], v[196:199], v[110:113]
	v_mfma_f32_16x16x32_bf16 v[106:109], v[164:167], v[196:199], v[106:109]
	s_barrier
	s_setprio 1
	s_waitcnt lgkmcnt(0)
	v_mfma_f32_16x16x32_bf16 v[94:97], v[146:149], v[204:207], v[94:97]
	v_mfma_f32_16x16x32_bf16 v[90:93], v[164:167], v[204:207], v[90:93]
	v_mfma_f32_16x16x32_bf16 v[78:81], v[146:149], v[218:221], v[78:81]
	v_mfma_f32_16x16x32_bf16 v[74:77], v[164:167], v[218:221], v[74:77]
	v_mfma_f32_16x16x32_bf16 v[126:129], v[160:163], v[192:195], v[126:129]
	v_mfma_f32_16x16x32_bf16 v[122:125], v[168:171], v[192:195], v[122:125]
	v_mfma_f32_16x16x32_bf16 v[110:113], v[160:163], v[200:203], v[110:113]
	v_mfma_f32_16x16x32_bf16 v[106:109], v[168:171], v[200:203], v[106:109]
	v_mfma_f32_16x16x32_bf16 v[94:97], v[160:163], v[208:211], v[94:97]
	v_mfma_f32_16x16x32_bf16 v[90:93], v[168:171], v[208:211], v[90:93]
	v_mfma_f32_16x16x32_bf16 v[78:81], v[160:163], v[226:229], v[78:81]
	v_mfma_f32_16x16x32_bf16 v[74:77], v[168:171], v[226:229], v[74:77]
	v_mfma_f32_16x16x32_bf16 v[118:121], v[172:175], v[188:191], v[118:121]
	v_mfma_f32_16x16x32_bf16 v[114:117], v[180:183], v[188:191], v[114:117]
	v_mfma_f32_16x16x32_bf16 v[102:105], v[172:175], v[196:199], v[102:105]
	v_mfma_f32_16x16x32_bf16 v[98:101], v[180:183], v[196:199], v[98:101]
	v_mfma_f32_16x16x32_bf16 v[86:89], v[172:175], v[204:207], v[86:89]
	v_mfma_f32_16x16x32_bf16 v[82:85], v[180:183], v[204:207], v[82:85]
	v_mfma_f32_16x16x32_bf16 v[70:73], v[172:175], v[218:221], v[70:73]
	v_mfma_f32_16x16x32_bf16 v[66:69], v[180:183], v[218:221], v[66:69]
	v_mfma_f32_16x16x32_bf16 v[118:121], v[176:179], v[192:195], v[118:121]
	v_mfma_f32_16x16x32_bf16 v[114:117], v[184:187], v[192:195], v[114:117]
	v_mfma_f32_16x16x32_bf16 v[102:105], v[176:179], v[200:203], v[102:105]
	v_mfma_f32_16x16x32_bf16 v[98:101], v[184:187], v[200:203], v[98:101]
	v_mfma_f32_16x16x32_bf16 v[86:89], v[176:179], v[208:211], v[86:89]
	v_mfma_f32_16x16x32_bf16 v[82:85], v[184:187], v[208:211], v[82:85]
	v_mfma_f32_16x16x32_bf16 v[70:73], v[176:179], v[226:229], v[70:73]
	v_mfma_f32_16x16x32_bf16 v[66:69], v[184:187], v[226:229], v[66:69]
	s_setprio 0
	s_barrier
	s_add_i32 s66, s50, s33
	v_lshl_add_u64 v[150:151], s[38:39], 0, v[132:133]
	s_mov_b32 m0, s66
	ds_read_b128 v[188:191], v159 offset:16384
	ds_read_b128 v[192:195], v159 offset:17408
	ds_read_b128 v[196:199], v159 offset:18432
	ds_read_b128 v[200:203], v159 offset:19456
	ds_read_b128 v[204:207], v159 offset:20480
	ds_read_b128 v[208:211], v159 offset:21504
	ds_read_b128 v[218:221], v159 offset:22528
	ds_read_b128 v[226:229], v159 offset:23552
	global_load_lds_dwordx4 v[150:151], off
	s_add_i32 m0, s66, 0x2000
	s_add_u32 s66, s38, 0x40000
	v_lshl_add_u64 v[214:215], s[38:39], 0, v[136:137]
	s_addc_u32 s67, s39, 0
	s_add_i32 s68, s51, s33
	global_load_lds_dwordx4 v[214:215], off
	v_lshl_add_u64 v[230:231], s[66:67], 0, v[132:133]
	s_mov_b32 m0, s68
	v_lshl_add_u64 v[232:233], s[40:41], 0, v[134:135]
	global_load_lds_dwordx4 v[230:231], off
	v_lshl_add_u64 v[230:231], s[66:67], 0, v[136:137]
	s_add_i32 m0, s68, 0x2000
	s_nop 0
	global_load_lds_dwordx4 v[230:231], off
	v_lshl_add_u64 v[230:231], s[40:41], 0, v[130:131]
	s_mov_b32 m0, s35
	s_nop 0
	global_load_lds_dwordx4 v[230:231], off
	s_mov_b32 m0, s42
	s_nop 0
	global_load_lds_dwordx4 v[232:233], off
	s_waitcnt vmcnt(8)
	s_waitcnt lgkmcnt(0)
	v_mfma_f32_16x16x32_bf16 v[62:65], v[146:149], v[188:191], v[62:65]
	v_mfma_f32_16x16x32_bf16 v[58:61], v[164:167], v[188:191], v[58:61]
	v_mfma_f32_16x16x32_bf16 v[46:49], v[146:149], v[196:199], v[46:49]
	v_mfma_f32_16x16x32_bf16 v[42:45], v[164:167], v[196:199], v[42:45]
	s_barrier
	s_setprio 1
	s_waitcnt lgkmcnt(0)
	v_mfma_f32_16x16x32_bf16 v[30:33], v[146:149], v[204:207], v[30:33]
	v_mfma_f32_16x16x32_bf16 v[26:29], v[164:167], v[204:207], v[26:29]
	v_mfma_f32_16x16x32_bf16 v[14:17], v[146:149], v[218:221], v[14:17]
	v_mfma_f32_16x16x32_bf16 v[10:13], v[164:167], v[218:221], v[10:13]
	v_mfma_f32_16x16x32_bf16 v[62:65], v[160:163], v[192:195], v[62:65]
	v_mfma_f32_16x16x32_bf16 v[58:61], v[168:171], v[192:195], v[58:61]
	v_mfma_f32_16x16x32_bf16 v[46:49], v[160:163], v[200:203], v[46:49]
	v_mfma_f32_16x16x32_bf16 v[42:45], v[168:171], v[200:203], v[42:45]
	v_mfma_f32_16x16x32_bf16 v[30:33], v[160:163], v[208:211], v[30:33]
	v_mfma_f32_16x16x32_bf16 v[26:29], v[168:171], v[208:211], v[26:29]
	v_mfma_f32_16x16x32_bf16 v[14:17], v[160:163], v[226:229], v[14:17]
	v_mfma_f32_16x16x32_bf16 v[10:13], v[168:171], v[226:229], v[10:13]
	v_mfma_f32_16x16x32_bf16 v[54:57], v[172:175], v[188:191], v[54:57]
	v_mfma_f32_16x16x32_bf16 v[50:53], v[180:183], v[188:191], v[50:53]
	v_mfma_f32_16x16x32_bf16 v[38:41], v[172:175], v[196:199], v[38:41]
	v_mfma_f32_16x16x32_bf16 v[34:37], v[180:183], v[196:199], v[34:37]
	v_mfma_f32_16x16x32_bf16 v[22:25], v[172:175], v[204:207], v[22:25]
	v_mfma_f32_16x16x32_bf16 v[18:21], v[180:183], v[204:207], v[18:21]
	v_mfma_f32_16x16x32_bf16 v[6:9], v[172:175], v[218:221], v[6:9]
	v_mfma_f32_16x16x32_bf16 v[2:5], v[180:183], v[218:221], v[2:5]
	v_mfma_f32_16x16x32_bf16 v[54:57], v[176:179], v[192:195], v[54:57]
	v_mfma_f32_16x16x32_bf16 v[50:53], v[184:187], v[192:195], v[50:53]
	v_mfma_f32_16x16x32_bf16 v[38:41], v[176:179], v[200:203], v[38:41]
	v_mfma_f32_16x16x32_bf16 v[34:37], v[184:187], v[200:203], v[34:37]
	v_mfma_f32_16x16x32_bf16 v[22:25], v[176:179], v[208:211], v[22:25]
	v_mfma_f32_16x16x32_bf16 v[18:21], v[184:187], v[208:211], v[18:21]
	v_mfma_f32_16x16x32_bf16 v[6:9], v[176:179], v[226:229], v[6:9]
	v_mfma_f32_16x16x32_bf16 v[2:5], v[184:187], v[226:229], v[2:5]
	s_setprio 0
	s_barrier
	s_add_i32 s66, 0, 0x18000
	s_add_i32 s67, 0, 0x1c000
	v_add_u32_e32 v168, s66, v153
	v_add_u32_e32 v184, s67, v153
	ds_read_b128 v[146:149], v168
	ds_read_b128 v[160:163], v168 offset:1024
	ds_read_b128 v[164:167], v168 offset:2048
	ds_read_b128 v[168:171], v168 offset:3072
	ds_read_b128 v[172:175], v184
	ds_read_b128 v[176:179], v184 offset:1024
	ds_read_b128 v[180:183], v184 offset:2048
	ds_read_b128 v[184:187], v184 offset:3072
	s_add_u32 s40, s40, 0x40000
	s_addc_u32 s41, s41, 0
	s_mov_b32 m0, s43
	v_lshl_add_u64 v[234:235], s[40:41], 0, v[130:131]
	ds_read_b128 v[188:191], v159 offset:32768
	ds_read_b128 v[192:195], v159 offset:33792
	ds_read_b128 v[196:199], v159 offset:34816
	ds_read_b128 v[200:203], v159 offset:35840
	ds_read_b128 v[204:207], v159 offset:36864
	ds_read_b128 v[208:211], v159 offset:37888
	ds_read_b128 v[218:221], v159 offset:38912
	ds_read_b128 v[226:229], v159 offset:39936
	global_load_lds_dwordx4 v[234:235], off
	v_lshl_add_u64 v[234:235], s[40:41], 0, v[134:135]
	s_mov_b32 m0, s44
	s_nop 0
	global_load_lds_dwordx4 v[234:235], off
	s_waitcnt vmcnt(8)
	s_waitcnt lgkmcnt(0)
	v_mfma_f32_16x16x32_bf16 v[126:129], v[146:149], v[188:191], v[126:129]
	v_mfma_f32_16x16x32_bf16 v[122:125], v[164:167], v[188:191], v[122:125]
	v_mfma_f32_16x16x32_bf16 v[110:113], v[146:149], v[196:199], v[110:113]
	v_mfma_f32_16x16x32_bf16 v[106:109], v[164:167], v[196:199], v[106:109]
	s_barrier
	s_setprio 1
	s_waitcnt lgkmcnt(0)
	v_mfma_f32_16x16x32_bf16 v[94:97], v[146:149], v[204:207], v[94:97]
	v_mfma_f32_16x16x32_bf16 v[90:93], v[164:167], v[204:207], v[90:93]
	v_mfma_f32_16x16x32_bf16 v[78:81], v[146:149], v[218:221], v[78:81]
	v_mfma_f32_16x16x32_bf16 v[74:77], v[164:167], v[218:221], v[74:77]
	v_mfma_f32_16x16x32_bf16 v[126:129], v[160:163], v[192:195], v[126:129]
	v_mfma_f32_16x16x32_bf16 v[122:125], v[168:171], v[192:195], v[122:125]
	v_mfma_f32_16x16x32_bf16 v[110:113], v[160:163], v[200:203], v[110:113]
	v_mfma_f32_16x16x32_bf16 v[106:109], v[168:171], v[200:203], v[106:109]
	v_mfma_f32_16x16x32_bf16 v[94:97], v[160:163], v[208:211], v[94:97]
	v_mfma_f32_16x16x32_bf16 v[90:93], v[168:171], v[208:211], v[90:93]
	v_mfma_f32_16x16x32_bf16 v[78:81], v[160:163], v[226:229], v[78:81]
	v_mfma_f32_16x16x32_bf16 v[74:77], v[168:171], v[226:229], v[74:77]
	v_mfma_f32_16x16x32_bf16 v[118:121], v[172:175], v[188:191], v[118:121]
	v_mfma_f32_16x16x32_bf16 v[114:117], v[180:183], v[188:191], v[114:117]
	v_mfma_f32_16x16x32_bf16 v[102:105], v[172:175], v[196:199], v[102:105]
	v_mfma_f32_16x16x32_bf16 v[98:101], v[180:183], v[196:199], v[98:101]
	v_mfma_f32_16x16x32_bf16 v[86:89], v[172:175], v[204:207], v[86:89]
	v_mfma_f32_16x16x32_bf16 v[82:85], v[180:183], v[204:207], v[82:85]
	v_mfma_f32_16x16x32_bf16 v[70:73], v[172:175], v[218:221], v[70:73]
	v_mfma_f32_16x16x32_bf16 v[66:69], v[180:183], v[218:221], v[66:69]
	v_mfma_f32_16x16x32_bf16 v[118:121], v[176:179], v[192:195], v[118:121]
	v_mfma_f32_16x16x32_bf16 v[114:117], v[184:187], v[192:195], v[114:117]
	v_mfma_f32_16x16x32_bf16 v[102:105], v[176:179], v[200:203], v[102:105]
	v_mfma_f32_16x16x32_bf16 v[98:101], v[184:187], v[200:203], v[98:101]
	v_mfma_f32_16x16x32_bf16 v[86:89], v[176:179], v[208:211], v[86:89]
	v_mfma_f32_16x16x32_bf16 v[82:85], v[184:187], v[208:211], v[82:85]
	v_mfma_f32_16x16x32_bf16 v[70:73], v[176:179], v[226:229], v[70:73]
	v_mfma_f32_16x16x32_bf16 v[66:69], v[184:187], v[226:229], v[66:69]
	s_setprio 0
	s_barrier
	s_add_i32 s40, s66, s33
	v_lshl_add_u64 v[150:151], v[150:151], 0, s[12:13]
	s_mov_b32 m0, s40
	ds_read_b128 v[188:191], v159 offset:49152
	ds_read_b128 v[192:195], v159 offset:50176
	ds_read_b128 v[196:199], v159 offset:51200
	ds_read_b128 v[200:203], v159 offset:52224
	ds_read_b128 v[204:207], v159 offset:53248
	ds_read_b128 v[208:211], v159 offset:54272
	ds_read_b128 v[218:221], v159 offset:55296
	ds_read_b128 v[226:229], v159 offset:56320
	global_load_lds_dwordx4 v[150:151], off
	s_add_i32 m0, s40, 0x2000
	s_add_u32 s38, s38, 0x40080
	v_lshl_add_u64 v[150:151], v[214:215], 0, s[12:13]
	s_addc_u32 s39, s39, 0
	s_add_i32 s40, s67, s33
	global_load_lds_dwordx4 v[150:151], off
	v_lshl_add_u64 v[150:151], s[38:39], 0, v[132:133]
	s_mov_b32 m0, s40
	s_nop 0
	global_load_lds_dwordx4 v[150:151], off
	v_lshl_add_u64 v[150:151], s[38:39], 0, v[136:137]
	s_add_i32 m0, s40, 0x2000
	s_nop 0
	global_load_lds_dwordx4 v[150:151], off
	v_lshl_add_u64 v[150:151], v[230:231], 0, s[12:13]
	s_mov_b32 m0, s46
	s_nop 0
	global_load_lds_dwordx4 v[150:151], off
	v_lshl_add_u64 v[150:151], v[232:233], 0, s[12:13]
	s_mov_b32 m0, s47
	s_nop 0
	global_load_lds_dwordx4 v[150:151], off
	s_waitcnt vmcnt(8)
	s_waitcnt lgkmcnt(0)
	v_mfma_f32_16x16x32_bf16 v[62:65], v[146:149], v[188:191], v[62:65]
	v_mfma_f32_16x16x32_bf16 v[58:61], v[164:167], v[188:191], v[58:61]
	v_mfma_f32_16x16x32_bf16 v[46:49], v[146:149], v[196:199], v[46:49]
	v_mfma_f32_16x16x32_bf16 v[42:45], v[164:167], v[196:199], v[42:45]
	s_barrier
	s_setprio 1
	s_waitcnt lgkmcnt(0)
	v_mfma_f32_16x16x32_bf16 v[30:33], v[146:149], v[204:207], v[30:33]
	v_mfma_f32_16x16x32_bf16 v[26:29], v[164:167], v[204:207], v[26:29]
	v_mfma_f32_16x16x32_bf16 v[14:17], v[146:149], v[218:221], v[14:17]
	v_mfma_f32_16x16x32_bf16 v[10:13], v[164:167], v[218:221], v[10:13]
	v_mfma_f32_16x16x32_bf16 v[62:65], v[160:163], v[192:195], v[62:65]
	v_mfma_f32_16x16x32_bf16 v[58:61], v[168:171], v[192:195], v[58:61]
	v_mfma_f32_16x16x32_bf16 v[46:49], v[160:163], v[200:203], v[46:49]
	v_mfma_f32_16x16x32_bf16 v[42:45], v[168:171], v[200:203], v[42:45]
	v_mfma_f32_16x16x32_bf16 v[30:33], v[160:163], v[208:211], v[30:33]
	v_mfma_f32_16x16x32_bf16 v[26:29], v[168:171], v[208:211], v[26:29]
	v_mfma_f32_16x16x32_bf16 v[14:17], v[160:163], v[226:229], v[14:17]
	v_mfma_f32_16x16x32_bf16 v[10:13], v[168:171], v[226:229], v[10:13]
	v_mfma_f32_16x16x32_bf16 v[54:57], v[172:175], v[188:191], v[54:57]
	v_mfma_f32_16x16x32_bf16 v[50:53], v[180:183], v[188:191], v[50:53]
	v_mfma_f32_16x16x32_bf16 v[38:41], v[172:175], v[196:199], v[38:41]
	v_mfma_f32_16x16x32_bf16 v[34:37], v[180:183], v[196:199], v[34:37]
	v_mfma_f32_16x16x32_bf16 v[22:25], v[172:175], v[204:207], v[22:25]
	v_mfma_f32_16x16x32_bf16 v[18:21], v[180:183], v[204:207], v[18:21]
	v_mfma_f32_16x16x32_bf16 v[6:9], v[172:175], v[218:221], v[6:9]
	v_mfma_f32_16x16x32_bf16 v[2:5], v[180:183], v[218:221], v[2:5]
	v_mfma_f32_16x16x32_bf16 v[54:57], v[176:179], v[192:195], v[54:57]
	v_mfma_f32_16x16x32_bf16 v[50:53], v[184:187], v[192:195], v[50:53]
	v_mfma_f32_16x16x32_bf16 v[38:41], v[176:179], v[200:203], v[38:41]
	v_mfma_f32_16x16x32_bf16 v[34:37], v[184:187], v[200:203], v[34:37]
	v_mfma_f32_16x16x32_bf16 v[22:25], v[176:179], v[208:211], v[22:25]
	v_mfma_f32_16x16x32_bf16 v[18:21], v[184:187], v[208:211], v[18:21]
	v_mfma_f32_16x16x32_bf16 v[6:9], v[176:179], v[226:229], v[6:9]
	v_mfma_f32_16x16x32_bf16 v[2:5], v[184:187], v[226:229], v[2:5]
	s_setprio 0
	s_barrier
	s_add_i32 s65, s65, 2
	s_add_u32 s36, s36, 0x100
	s_addc_u32 s37, s37, 0
	s_add_u32 s61, s61, 0x100
	s_addc_u32 s64, s64, 0
	s_cmp_gt_u32 s65, 13
	s_cbranch_scc0 .LBB0_1753
	s_and_b64 vcc, exec, s[14:15]
	s_cbranch_vccz .LBB0_1756
	s_barrier

.LBB0_1864:
	v_add_u32_e32 v131, s47, v151
	ds_read_b128 v[154:157], v131
	ds_read_b128 v[158:161], v131 offset:1024
	ds_read_b128 v[162:165], v131 offset:2048
	ds_read_b128 v[166:169], v131 offset:3072
	v_add_u32_e32 v131, s48, v151
	ds_read_b128 v[170:173], v131
	ds_read_b128 v[174:177], v131 offset:1024
	ds_read_b128 v[178:181], v131 offset:2048
	ds_read_b128 v[182:185], v131 offset:3072
	s_add_i32 s55, s28, 2
	s_add_u32 s58, s26, 0x80
	s_addc_u32 s29, s27, 0
	s_cmp_eq_u32 s46, s28
	s_cselect_b32 s28, s6, s58
	s_cselect_b32 s29, s7, s29
	s_cselect_b32 s59, s25, s54
	s_cselect_b32 s58, s24, s53
	v_lshl_add_u64 v[132:133], s[26:27], 0, v[142:143]
	s_add_i32 m0, s38, 0xc000
	ds_read_b128 v[186:189], v152
	ds_read_b128 v[194:197], v152 offset:1024
	ds_read_b128 v[198:201], v152 offset:2048
	ds_read_b128 v[202:205], v152 offset:3072
	ds_read_b128 v[206:209], v152 offset:4096
	ds_read_b128 v[218:221], v152 offset:5120
	ds_read_b128 v[226:229], v152 offset:6144
	ds_read_b128 v[230:233], v152 offset:7168
	global_load_lds_dwordx4 v[132:133], off
	v_lshl_add_u64 v[132:133], s[26:27], 0, v[144:145]
	s_add_i32 m0, s38, 0xe000
	s_nop 0
	global_load_lds_dwordx4 v[132:133], off
	s_waitcnt vmcnt(8)
	s_waitcnt lgkmcnt(0)
	v_mfma_f32_16x16x32_bf16 v[122:125], v[154:157], v[186:189], v[122:125]
	v_mfma_f32_16x16x32_bf16 v[126:129], v[162:165], v[186:189], v[126:129]
	v_mfma_f32_16x16x32_bf16 v[114:117], v[154:157], v[198:201], v[114:117]
	v_mfma_f32_16x16x32_bf16 v[118:121], v[162:165], v[198:201], v[118:121]
	s_barrier
	s_setprio 1
	s_waitcnt lgkmcnt(0)
	v_mfma_f32_16x16x32_bf16 v[94:97], v[154:157], v[206:209], v[94:97]
	v_mfma_f32_16x16x32_bf16 v[90:93], v[162:165], v[206:209], v[90:93]
	v_mfma_f32_16x16x32_bf16 v[78:81], v[154:157], v[226:229], v[78:81]
	v_mfma_f32_16x16x32_bf16 v[74:77], v[162:165], v[226:229], v[74:77]
	v_mfma_f32_16x16x32_bf16 v[122:125], v[158:161], v[194:197], v[122:125]
	v_mfma_f32_16x16x32_bf16 v[126:129], v[166:169], v[194:197], v[126:129]
	v_mfma_f32_16x16x32_bf16 v[114:117], v[158:161], v[202:205], v[114:117]
	v_mfma_f32_16x16x32_bf16 v[118:121], v[166:169], v[202:205], v[118:121]
	v_mfma_f32_16x16x32_bf16 v[94:97], v[158:161], v[218:221], v[94:97]
	v_mfma_f32_16x16x32_bf16 v[90:93], v[166:169], v[218:221], v[90:93]
	v_mfma_f32_16x16x32_bf16 v[78:81], v[158:161], v[230:233], v[78:81]
	v_mfma_f32_16x16x32_bf16 v[74:77], v[166:169], v[230:233], v[74:77]
	v_mfma_f32_16x16x32_bf16 v[110:113], v[170:173], v[186:189], v[110:113]
	v_mfma_f32_16x16x32_bf16 v[106:109], v[178:181], v[186:189], v[106:109]
	v_mfma_f32_16x16x32_bf16 v[102:105], v[170:173], v[198:201], v[102:105]
	v_mfma_f32_16x16x32_bf16 v[98:101], v[178:181], v[198:201], v[98:101]
	v_mfma_f32_16x16x32_bf16 v[86:89], v[170:173], v[206:209], v[86:89]
	v_mfma_f32_16x16x32_bf16 v[82:85], v[178:181], v[206:209], v[82:85]
	v_mfma_f32_16x16x32_bf16 v[70:73], v[170:173], v[226:229], v[70:73]
	v_mfma_f32_16x16x32_bf16 v[66:69], v[178:181], v[226:229], v[66:69]
	v_mfma_f32_16x16x32_bf16 v[110:113], v[174:177], v[194:197], v[110:113]
	v_mfma_f32_16x16x32_bf16 v[106:109], v[182:185], v[194:197], v[106:109]
	v_mfma_f32_16x16x32_bf16 v[102:105], v[174:177], v[202:205], v[102:105]
	v_mfma_f32_16x16x32_bf16 v[98:101], v[182:185], v[202:205], v[98:101]
	v_mfma_f32_16x16x32_bf16 v[86:89], v[174:177], v[218:221], v[86:89]
	v_mfma_f32_16x16x32_bf16 v[82:85], v[182:185], v[218:221], v[82:85]
	v_mfma_f32_16x16x32_bf16 v[70:73], v[174:177], v[230:233], v[70:73]
	v_mfma_f32_16x16x32_bf16 v[66:69], v[182:185], v[230:233], v[66:69]
	s_setprio 0
	s_barrier
	s_add_i32 s60, s47, s34
	v_lshl_add_u64 v[132:133], s[58:59], 0, v[136:137]
	s_mov_b32 m0, s60
	ds_read_b128 v[186:189], v152 offset:16384
	ds_read_b128 v[194:197], v152 offset:17408
	ds_read_b128 v[198:201], v152 offset:18432
	ds_read_b128 v[202:205], v152 offset:19456
	ds_read_b128 v[206:209], v152 offset:20480
	ds_read_b128 v[218:221], v152 offset:21504
	ds_read_b128 v[226:229], v152 offset:22528
	ds_read_b128 v[230:233], v152 offset:23552
	global_load_lds_dwordx4 v[132:133], off
	s_add_i32 m0, s60, 0x2000
	v_lshl_add_u64 v[190:191], s[58:59], 0, v[140:141]
	s_add_u32 s58, s58, s12
	s_addc_u32 s59, s59, s13
	s_add_i32 s60, s48, s34
	global_load_lds_dwordx4 v[190:191], off
	v_lshl_add_u64 v[210:211], s[58:59], 0, v[136:137]
	s_mov_b32 m0, s60
	v_lshl_add_u64 v[234:235], s[58:59], 0, v[140:141]
	global_load_lds_dwordx4 v[210:211], off
	s_add_i32 m0, s60, 0x2000
	v_lshl_add_u64 v[236:237], s[28:29], 0, v[134:135]
	global_load_lds_dwordx4 v[234:235], off
	s_mov_b32 m0, s38
	v_lshl_add_u64 v[238:239], s[28:29], 0, v[138:139]
	global_load_lds_dwordx4 v[236:237], off
	s_mov_b32 m0, s39
	s_nop 0
	global_load_lds_dwordx4 v[238:239], off
	s_waitcnt vmcnt(8)
	s_waitcnt lgkmcnt(0)
	v_mfma_f32_16x16x32_bf16 v[62:65], v[154:157], v[186:189], v[62:65]
	v_mfma_f32_16x16x32_bf16 v[58:61], v[162:165], v[186:189], v[58:61]
	v_mfma_f32_16x16x32_bf16 v[46:49], v[154:157], v[198:201], v[46:49]
	v_mfma_f32_16x16x32_bf16 v[42:45], v[162:165], v[198:201], v[42:45]
	s_barrier
	s_setprio 1
	s_waitcnt lgkmcnt(0)
	v_mfma_f32_16x16x32_bf16 v[30:33], v[154:157], v[206:209], v[30:33]
	v_mfma_f32_16x16x32_bf16 v[26:29], v[162:165], v[206:209], v[26:29]
	v_mfma_f32_16x16x32_bf16 v[14:17], v[154:157], v[226:229], v[14:17]
	v_mfma_f32_16x16x32_bf16 v[10:13], v[162:165], v[226:229], v[10:13]
	v_mfma_f32_16x16x32_bf16 v[62:65], v[158:161], v[194:197], v[62:65]
	v_mfma_f32_16x16x32_bf16 v[58:61], v[166:169], v[194:197], v[58:61]
	v_mfma_f32_16x16x32_bf16 v[46:49], v[158:161], v[202:205], v[46:49]
	v_mfma_f32_16x16x32_bf16 v[42:45], v[166:169], v[202:205], v[42:45]
	v_mfma_f32_16x16x32_bf16 v[30:33], v[158:161], v[218:221], v[30:33]
	v_mfma_f32_16x16x32_bf16 v[26:29], v[166:169], v[218:221], v[26:29]
	v_mfma_f32_16x16x32_bf16 v[14:17], v[158:161], v[230:233], v[14:17]
	v_mfma_f32_16x16x32_bf16 v[10:13], v[166:169], v[230:233], v[10:13]
	v_mfma_f32_16x16x32_bf16 v[54:57], v[170:173], v[186:189], v[54:57]
	v_mfma_f32_16x16x32_bf16 v[50:53], v[178:181], v[186:189], v[50:53]
	v_mfma_f32_16x16x32_bf16 v[38:41], v[170:173], v[198:201], v[38:41]
	v_mfma_f32_16x16x32_bf16 v[34:37], v[178:181], v[198:201], v[34:37]
	v_mfma_f32_16x16x32_bf16 v[22:25], v[170:173], v[206:209], v[22:25]
	v_mfma_f32_16x16x32_bf16 v[18:21], v[178:181], v[206:209], v[18:21]
	v_mfma_f32_16x16x32_bf16 v[6:9], v[170:173], v[226:229], v[6:9]
	v_mfma_f32_16x16x32_bf16 v[2:5], v[178:181], v[226:229], v[2:5]
	v_mfma_f32_16x16x32_bf16 v[54:57], v[174:177], v[194:197], v[54:57]
	v_mfma_f32_16x16x32_bf16 v[50:53], v[182:185], v[194:197], v[50:53]
	v_mfma_f32_16x16x32_bf16 v[38:41], v[174:177], v[202:205], v[38:41]
	v_mfma_f32_16x16x32_bf16 v[34:37], v[182:185], v[202:205], v[34:37]
	v_mfma_f32_16x16x32_bf16 v[22:25], v[174:177], v[218:221], v[22:25]
	v_mfma_f32_16x16x32_bf16 v[18:21], v[182:185], v[218:221], v[18:21]
	v_mfma_f32_16x16x32_bf16 v[6:9], v[174:177], v[230:233], v[6:9]
	v_mfma_f32_16x16x32_bf16 v[2:5], v[182:185], v[230:233], v[2:5]
	s_setprio 0
	s_barrier
	s_add_i32 s58, 0, 0x18000
	v_add_u32_e32 v131, s58, v151
	s_add_i32 s59, 0, 0x1c000
	ds_read_b128 v[154:157], v131
	ds_read_b128 v[158:161], v131 offset:1024
	ds_read_b128 v[162:165], v131 offset:2048
	ds_read_b128 v[166:169], v131 offset:3072
	v_add_u32_e32 v131, s59, v151
	ds_read_b128 v[170:173], v131
	ds_read_b128 v[174:177], v131 offset:1024
	ds_read_b128 v[178:181], v131 offset:2048
	ds_read_b128 v[182:185], v131 offset:3072
	s_add_u32 s28, s28, s12
	s_addc_u32 s29, s29, s13
	s_mov_b32 m0, s40
	v_lshl_add_u64 v[240:241], s[28:29], 0, v[134:135]
	ds_read_b128 v[186:189], v152 offset:32768
	ds_read_b128 v[194:197], v152 offset:33792
	ds_read_b128 v[198:201], v152 offset:34816
	ds_read_b128 v[202:205], v152 offset:35840
	ds_read_b128 v[206:209], v152 offset:36864
	ds_read_b128 v[218:221], v152 offset:37888
	ds_read_b128 v[226:229], v152 offset:38912
	ds_read_b128 v[230:233], v152 offset:39936
	global_load_lds_dwordx4 v[240:241], off
	v_lshl_add_u64 v[240:241], s[28:29], 0, v[138:139]
	s_mov_b32 m0, s41
	s_nop 0
	global_load_lds_dwordx4 v[240:241], off
	s_waitcnt vmcnt(8)
	s_waitcnt lgkmcnt(0)
	v_mfma_f32_16x16x32_bf16 v[122:125], v[154:157], v[186:189], v[122:125]
	v_mfma_f32_16x16x32_bf16 v[126:129], v[162:165], v[186:189], v[126:129]
	v_mfma_f32_16x16x32_bf16 v[114:117], v[154:157], v[198:201], v[114:117]
	v_mfma_f32_16x16x32_bf16 v[118:121], v[162:165], v[198:201], v[118:121]
	s_barrier
	s_setprio 1
	s_waitcnt lgkmcnt(0)
	v_mfma_f32_16x16x32_bf16 v[94:97], v[154:157], v[206:209], v[94:97]
	v_mfma_f32_16x16x32_bf16 v[90:93], v[162:165], v[206:209], v[90:93]
	v_mfma_f32_16x16x32_bf16 v[78:81], v[154:157], v[226:229], v[78:81]
	v_mfma_f32_16x16x32_bf16 v[74:77], v[162:165], v[226:229], v[74:77]
	v_mfma_f32_16x16x32_bf16 v[122:125], v[158:161], v[194:197], v[122:125]
	v_mfma_f32_16x16x32_bf16 v[126:129], v[166:169], v[194:197], v[126:129]
	v_mfma_f32_16x16x32_bf16 v[114:117], v[158:161], v[202:205], v[114:117]
	v_mfma_f32_16x16x32_bf16 v[118:121], v[166:169], v[202:205], v[118:121]
	v_mfma_f32_16x16x32_bf16 v[94:97], v[158:161], v[218:221], v[94:97]
	v_mfma_f32_16x16x32_bf16 v[90:93], v[166:169], v[218:221], v[90:93]
	v_mfma_f32_16x16x32_bf16 v[78:81], v[158:161], v[230:233], v[78:81]
	v_mfma_f32_16x16x32_bf16 v[74:77], v[166:169], v[230:233], v[74:77]
	v_mfma_f32_16x16x32_bf16 v[110:113], v[170:173], v[186:189], v[110:113]
	v_mfma_f32_16x16x32_bf16 v[106:109], v[178:181], v[186:189], v[106:109]
	v_mfma_f32_16x16x32_bf16 v[102:105], v[170:173], v[198:201], v[102:105]
	v_mfma_f32_16x16x32_bf16 v[98:101], v[178:181], v[198:201], v[98:101]
	v_mfma_f32_16x16x32_bf16 v[86:89], v[170:173], v[206:209], v[86:89]
	v_mfma_f32_16x16x32_bf16 v[82:85], v[178:181], v[206:209], v[82:85]
	v_mfma_f32_16x16x32_bf16 v[70:73], v[170:173], v[226:229], v[70:73]
	v_mfma_f32_16x16x32_bf16 v[66:69], v[178:181], v[226:229], v[66:69]
	v_mfma_f32_16x16x32_bf16 v[110:113], v[174:177], v[194:197], v[110:113]
	v_mfma_f32_16x16x32_bf16 v[106:109], v[182:185], v[194:197], v[106:109]
	v_mfma_f32_16x16x32_bf16 v[102:105], v[174:177], v[202:205], v[102:105]
	v_mfma_f32_16x16x32_bf16 v[98:101], v[182:185], v[202:205], v[98:101]
	v_mfma_f32_16x16x32_bf16 v[86:89], v[174:177], v[218:221], v[86:89]
	v_mfma_f32_16x16x32_bf16 v[82:85], v[182:185], v[218:221], v[82:85]
	v_mfma_f32_16x16x32_bf16 v[70:73], v[174:177], v[230:233], v[70:73]
	v_mfma_f32_16x16x32_bf16 v[66:69], v[182:185], v[230:233], v[66:69]
	s_setprio 0
	s_barrier
	s_add_i32 s28, s58, s34
	v_lshl_add_u64 v[132:133], v[132:133], 0, s[20:21]
	s_mov_b32 m0, s28
	ds_read_b128 v[186:189], v152 offset:49152
	ds_read_b128 v[194:197], v152 offset:50176
	ds_read_b128 v[198:201], v152 offset:51200
	ds_read_b128 v[202:205], v152 offset:52224
	ds_read_b128 v[206:209], v152 offset:53248
	ds_read_b128 v[218:221], v152 offset:54272
	ds_read_b128 v[226:229], v152 offset:55296
	ds_read_b128 v[230:233], v152 offset:56320
	global_load_lds_dwordx4 v[132:133], off
	v_lshl_add_u64 v[132:133], v[190:191], 0, s[20:21]
	s_add_i32 m0, s28, 0x2000
	s_add_i32 s28, s59, s34
	global_load_lds_dwordx4 v[132:133], off
	v_lshl_add_u64 v[132:133], v[210:211], 0, s[20:21]
	s_mov_b32 m0, s28
	s_nop 0
	global_load_lds_dwordx4 v[132:133], off
	v_lshl_add_u64 v[132:133], v[234:235], 0, s[20:21]
	s_add_i32 m0, s28, 0x2000
	s_nop 0
	global_load_lds_dwordx4 v[132:133], off
	v_lshl_add_u64 v[132:133], v[236:237], 0, s[20:21]
	s_mov_b32 m0, s42
	s_nop 0
	global_load_lds_dwordx4 v[132:133], off
	v_lshl_add_u64 v[132:133], v[238:239], 0, s[20:21]
	s_mov_b32 m0, s43
	s_nop 0
	global_load_lds_dwordx4 v[132:133], off
	s_waitcnt vmcnt(8)
	s_waitcnt lgkmcnt(0)
	v_mfma_f32_16x16x32_bf16 v[62:65], v[154:157], v[186:189], v[62:65]
	v_mfma_f32_16x16x32_bf16 v[58:61], v[162:165], v[186:189], v[58:61]
	v_mfma_f32_16x16x32_bf16 v[46:49], v[154:157], v[198:201], v[46:49]
	v_mfma_f32_16x16x32_bf16 v[42:45], v[162:165], v[198:201], v[42:45]
	s_barrier
	s_setprio 1
	s_waitcnt lgkmcnt(0)
	v_mfma_f32_16x16x32_bf16 v[30:33], v[154:157], v[206:209], v[30:33]
	v_mfma_f32_16x16x32_bf16 v[26:29], v[162:165], v[206:209], v[26:29]
	v_mfma_f32_16x16x32_bf16 v[14:17], v[154:157], v[226:229], v[14:17]
	v_mfma_f32_16x16x32_bf16 v[10:13], v[162:165], v[226:229], v[10:13]
	v_mfma_f32_16x16x32_bf16 v[62:65], v[158:161], v[194:197], v[62:65]
	v_mfma_f32_16x16x32_bf16 v[58:61], v[166:169], v[194:197], v[58:61]
	v_mfma_f32_16x16x32_bf16 v[46:49], v[158:161], v[202:205], v[46:49]
	v_mfma_f32_16x16x32_bf16 v[42:45], v[166:169], v[202:205], v[42:45]
	v_mfma_f32_16x16x32_bf16 v[30:33], v[158:161], v[218:221], v[30:33]
	v_mfma_f32_16x16x32_bf16 v[26:29], v[166:169], v[218:221], v[26:29]
	v_mfma_f32_16x16x32_bf16 v[14:17], v[158:161], v[230:233], v[14:17]
	v_mfma_f32_16x16x32_bf16 v[10:13], v[166:169], v[230:233], v[10:13]
	v_mfma_f32_16x16x32_bf16 v[54:57], v[170:173], v[186:189], v[54:57]
	v_mfma_f32_16x16x32_bf16 v[50:53], v[178:181], v[186:189], v[50:53]
	v_mfma_f32_16x16x32_bf16 v[38:41], v[170:173], v[198:201], v[38:41]
	v_mfma_f32_16x16x32_bf16 v[34:37], v[178:181], v[198:201], v[34:37]
	v_mfma_f32_16x16x32_bf16 v[22:25], v[170:173], v[206:209], v[22:25]
	v_mfma_f32_16x16x32_bf16 v[18:21], v[178:181], v[206:209], v[18:21]
	v_mfma_f32_16x16x32_bf16 v[6:9], v[170:173], v[226:229], v[6:9]
	v_mfma_f32_16x16x32_bf16 v[2:5], v[178:181], v[226:229], v[2:5]
	v_mfma_f32_16x16x32_bf16 v[54:57], v[174:177], v[194:197], v[54:57]
	v_mfma_f32_16x16x32_bf16 v[50:53], v[182:185], v[194:197], v[50:53]
	v_mfma_f32_16x16x32_bf16 v[38:41], v[174:177], v[202:205], v[38:41]
	v_mfma_f32_16x16x32_bf16 v[34:37], v[182:185], v[202:205], v[34:37]
	v_mfma_f32_16x16x32_bf16 v[22:25], v[174:177], v[218:221], v[22:25]
	v_mfma_f32_16x16x32_bf16 v[18:21], v[182:185], v[218:221], v[18:21]
	v_mfma_f32_16x16x32_bf16 v[6:9], v[174:177], v[230:233], v[6:9]
	v_mfma_f32_16x16x32_bf16 v[2:5], v[182:185], v[230:233], v[2:5]
	s_setprio 0
	s_barrier
	s_add_u32 s26, s26, 0x100
	s_addc_u32 s27, s27, 0
	s_add_u32 s53, s53, 0x100
	s_addc_u32 s54, s54, 0
	s_cmp_ge_i32 s55, s45
	s_mov_b32 s28, s55
	s_cbranch_scc0 .LBB0_1864
